# vp56 plus instruction selection: the 32 flat_load/flat_store ops of the attention prologue and epilogue converted to global_load/global_store
# speedup vs baseline: 1.0035x; 1.0035x over previous
;   #define CMASK(P0,P1,t) do{}while(0)
; template<int THRL> __device__ __forceinline__ void attn_unit(int b,int h,int qb,unsigned char*wsb,char*shm,float kmax,const int CMB,float lam){
;   const bf16*Q,*K,*V; { unsigned char*w_=wsb; asm volatile("":"+s"(w_)); Q=(const bf16*)(w_+AWS_Q); K=(const bf16*)(w_+AWS_K); V=(const bf16*)(w_+AWS_V); }
;   constexpr int ya_pitch=2048;
;   const int tid=tid_now(),lane=tid&63,r32=lane&31,hi=lane>>5; const int wid=__builtin_amdgcn_readfirstlane(tid>>6);
;   const long rowbase=(long)b*SEQ; const int q0=qb*QB;
;   const bf16*Qw=Q+(rowbase+q0+wid*QBLK)*DM+h*D;
;   const bf16*Kh=K+rowbase*DM+h*D,*Vh=V+rowbase*DM+(h&~1)*D;
;   const unsigned lds0=(unsigned)(uintptr_t)shm;
;   float*wsf=(float*)(shm+LDS_WS)+wid*64;
;   const bf16*ksrc=Kh+(long)lane*DM+wid*8;
;   const bf16*vsrc=Vh+(long)(16*(wid&3)+(lane>>2))*DM+(wid>>2)*32+(lane&3)*8;
;   const unsigned kdst=lds0+LDS_K+wid*1024, vdst=lds0+LDS_V+wid*1024, vdst2=lds0+LDS_V2+wid*1024;
;     ...
;   const int vb0=(int)(lds0+LDS_V)+((lane>>4)&1)*32+(lane&3)*8+(4*hi+((lane&15)>>2))*64;
;   const char*Kbase=shm+LDS_K; bf16x8 kf[8];
;   const lds_cptr shm3=(lds_cptr)shm; const lds_cptr kp0=shm3+LDS_K+hi*1024+r32*16; const lds_cptr vp0=shm3+LDS_V+((lane>>4)&1)*32+(lane&3)*8+(4*hi+((lane&15)>>2))*64;
;   const int NT=(q0+QB)/KVBLK;
;   DMA_K(0,0);DMA_V(0,0);DMA_K(1,SLOTB);
;   bf16x8 qr[4];
;   #pragma unroll
;   for(int d0=0;d0<4;++d0)qr[d0]=*reinterpret_cast<const bf16x8*>(&Qw[(long)r32*DM+d0*16+hi*8]);
;   float q2_=0.f;
;   #pragma unroll
;   for(int d0=0;d0<4;++d0){const u32x4 w_=__builtin_bit_cast(u32x4,qr[d0]);
;     #pragma unroll
;     for(int e=0;e<4;++e){const float lo_=__uint_as_float(w_[e]<<16),hi_=__uint_as_float(w_[e]&0xffff0000u);q2_+=lo_*lo_+hi_*hi_;}}
;   {auto rr=__builtin_amdgcn_permlane32_swap(__float_as_uint(q2_),__float_as_uint(q2_),false,false);q2_=__uint_as_float(rr[0])+__uint_as_float(rr[1]);}
;   const float mhat=sqrtf(q2_)*kmax*1.004f+0.02f;
;   float l_reg=0.f;f32x16 o[2];o[0]=f32x16{};o[1]=f32x16{};f32x16 o2[2];o2[0]=f32x16{};o2[1]=f32x16{};const f32x16 negm=f32x16{};
;   const int qrel=wid*QBLK+r32;
;     ...
;   bool resc=false;
;     ...
;   f32x16 pA0,pA1,pB0,pB1;
;   int sl_prev=0,sl_cur=0,sl_next=SLOTB;
;     ...
;   DMA_K(2,2*SLOTB);
;   WAIT_BAR(4);
;   qkt(pA0,pA1,Kbase,qr,negm,r32,hi);asm volatile("s_nop 15\n\ts_nop 7":"+v"(pA0),"+v"(pA1));CMASK(pA0,pA1,0);
.LBB0_307:
	s_or_b32 s1, s43, s81
	s_lshl_b32 s3, s1, 1
	s_or_b32 s4, s3, s82
	s_ashr_i32 s5, s4, 31
	s_lshl_b64 s[4:5], s[4:5], 2
	s_add_u32 s4, s72, s4
	s_addc_u32 s5, s73, s5
	s_mov_b64 s[64:65], s[8:9]
	s_waitcnt lgkmcnt(0)
	v_mov_b32_e32 v36, v230
	global_load_dword v6, v221, s[4:5] sc1
	global_load_dword v7, v221, s[4:5] offset:4 sc1
	v_mov_b32_e32 v3, v221
	v_readfirstlane_b32 s95, v36
	s_ashr_i32 s94, s95, 6
	s_lshl_b32 s4, s94, 5
	s_ashr_i32 s3, s4, 31
	s_add_u32 s56, s87, s4
	s_addc_u32 s57, s88, s3
	s_lshl_b64 s[36:37], s[56:57], 11
	s_add_u32 s3, s64, s36
	s_addc_u32 s5, s65, s37
	s_lshl_b32 s93, s1, 6
	s_lshl_b32 s1, s1, 7
	s_add_u32 s36, s3, s1
	s_addc_u32 s37, s5, 0
	s_add_u32 s3, s64, s50
	s_addc_u32 s5, s65, s51
	s_add_u32 s60, s3, s1
	s_addc_u32 s61, s5, 0
	s_and_b32 s1, s93, 0x380
	s_lshl_b32 s92, s1, 1
	s_add_u32 s62, s3, s92
	s_addc_u32 s63, s5, 0
	s_lshl_b32 s1, s94, 4
	v_bfe_u32 v214, v36, 2, 4
	v_and_b32_e32 v241, 63, v36
	v_and_or_b32 v2, s1, 48, v214
	s_ashr_i32 s1, s95, 3
	v_lshlrev_b32_e32 v220, 11, v241
	s_lshl_b32 s66, s94, 3
	v_lshlrev_b32_e32 v2, 11, v2
	s_and_b32 s68, s1, 0xffffffe0
	v_lshlrev_b32_e32 v244, 3, v36
	v_lshl_add_u64 v[0:1], s[60:61], 0, v[220:221]
	s_ashr_i32 s67, s66, 31
	v_lshl_add_u64 v[2:3], s[62:63], 0, v[2:3]
	s_ashr_i32 s69, s68, 31
	v_and_b32_e32 v249, 24, v244
	s_lshl_b32 s1, s94, 10
	v_lshl_add_u64 v[0:1], s[66:67], 1, v[0:1]
	s_mov_b64 s[60:61], 0x14000000
	v_lshl_add_u64 v[2:3], s[68:69], 1, v[2:3]
	v_lshlrev_b32_e32 v4, 1, v249
	v_mov_b32_e32 v5, v221
	s_cmp_lg_u32 0, -1
	v_lshl_add_u64 v[32:33], v[0:1], 0, s[60:61]
	v_lshl_add_u64 v[2:3], v[2:3], 0, v[4:5]
	s_mov_b64 s[60:61], 0x18000000
	s_cselect_b32 s3, 0, 0
	v_lshl_add_u64 v[34:35], v[2:3], 0, s[60:61]
	s_add_i32 s3, s1, s3
	s_mov_b32 s5, m0
	s_mov_b32 m0, s3
	s_nop 0
	global_load_lds_dwordx4 v[32:33], off
	s_mov_b32 m0, s5
	s_mov_b64 s[60:61], 0x18000080
	s_add_i32 s97, s3, 0x6000
	s_mov_b32 s5, m0
	s_mov_b32 m0, s97
	s_nop 0
	global_load_lds_dwordx4 v[34:35], off
	s_mov_b32 m0, s5
	v_lshl_add_u64 v[2:3], v[2:3], 0, s[60:61]
	s_mov_b64 s[60:61], 0x14020000
	v_and_b32_e32 v243, 31, v36
	s_add_i32 s96, s3, 0xc000
	s_mov_b32 s5, m0
	s_mov_b32 m0, s96
	s_nop 0
	global_load_lds_dwordx4 v[2:3], off
	s_mov_b32 m0, s5
	v_lshl_add_u64 v[2:3], v[0:1], 0, s[60:61]
	v_bfe_u32 v242, v36, 5, 1
	s_add_i32 s5, s3, 0x2000
	s_mov_b32 s6, m0
	s_mov_b32 m0, s5
	s_nop 0
	global_load_lds_dwordx4 v[2:3], off
	s_mov_b32 m0, s6
	v_lshlrev_b32_e32 v2, 11, v243
	v_lshl_or_b32 v2, v242, 4, v2
	v_mov_b32_e32 v3, v221
	v_lshl_add_u64 v[2:3], s[36:37], 0, v[2:3]
	s_brev_b32 s5, 8
	v_add_co_u32_e32 v4, vcc, s5, v2
	s_mov_b64 s[36:37], 0x10000000
	s_nop 0
	v_addc_co_u32_e32 v5, vcc, 0, v3, vcc
	global_load_dwordx4 v[156:159], v[4:5], off
	v_lshl_add_u64 v[2:3], v[2:3], 0, s[36:37]
	global_load_dwordx4 v[152:155], v[2:3], off offset:32
	global_load_dwordx4 v[148:151], v[2:3], off offset:64
	global_load_dwordx4 v[144:147], v[2:3], off offset:96
	v_lshlrev_b32_e32 v2, 10, v242
	v_lshlrev_b32_e32 v3, 4, v243
	v_add3_u32 v250, 0, v2, v3
	s_waitcnt vmcnt(0)
	v_readfirstlane_b32 s6, v7
	v_readfirstlane_b32 s5, v6
	s_mov_b64 s[36:37], 0x14040000
	v_lshl_add_u64 v[0:1], v[0:1], 0, s[36:37]
	s_add_i32 s33, s3, 0x4000
	s_mov_b32 s36, m0
	s_mov_b32 m0, s33
	s_nop 0
	global_load_lds_dwordx4 v[0:1], off
	s_mov_b32 m0, s36
	s_waitcnt vmcnt(4) lgkmcnt(0)
	s_barrier
	v_or_b32_e32 v248, s4, v243
	s_andn2_b64 vcc, exec, s[52:53]
	v_lshlrev_b32_e32 v245, 2, v242
	s_waitcnt lgkmcnt(0)
	v_and_b32_e32 v11, 0xffff0000, v152
	v_and_b32_e32 v3, 0xffff0000, v156
	v_and_b32_e32 v5, 0xffff0000, v157
	v_lshlrev_b32_e32 v2, 16, v156
	v_lshlrev_b32_e32 v4, 16, v157
	v_and_b32_e32 v7, 0xffff0000, v158
	v_mul_f32_e32 v3, v3, v3
	v_mul_f32_e32 v5, v5, v5
	v_lshlrev_b32_e32 v6, 16, v158
	v_and_b32_e32 v9, 0xffff0000, v159
	v_mul_f32_e32 v7, v7, v7
	v_fmac_f32_e32 v3, v2, v2
	v_fmac_f32_e32 v5, v4, v4
	v_lshlrev_b32_e32 v8, 16, v159
	v_mul_f32_e32 v9, v9, v9
	v_fmac_f32_e32 v7, v6, v6
	v_add_f32_e32 v2, v3, v5
	v_lshlrev_b32_e32 v10, 16, v152
	v_and_b32_e32 v13, 0xffff0000, v153
	v_mul_f32_e32 v11, v11, v11
	v_fmac_f32_e32 v9, v8, v8
	v_add_f32_e32 v2, v7, v2
	v_lshlrev_b32_e32 v12, 16, v153
	v_mul_f32_e32 v13, v13, v13
	v_fmac_f32_e32 v11, v10, v10
	v_add_f32_e32 v2, v9, v2
	v_fmac_f32_e32 v13, v12, v12
	v_add_f32_e32 v2, v11, v2
	v_add_f32_e32 v4, v13, v2
	ds_read_b128 v[16:19], v250 offset:512
	ds_read_b128 v[0:3], v250
	v_and_b32_e32 v15, 0xffff0000, v154
	v_lshlrev_b32_e32 v14, 16, v154
	v_mul_f32_e32 v15, v15, v15
	v_and_b32_e32 v6, 0xffff0000, v155
	v_fmac_f32_e32 v15, v14, v14
	v_lshlrev_b32_e32 v5, 16, v155
	v_mul_f32_e32 v6, v6, v6
	v_add_f32_e32 v4, v15, v4
	v_fmac_f32_e32 v6, v5, v5
	v_add_f32_e32 v20, v6, v4
	s_waitcnt lgkmcnt(0)
	v_mfma_f32_32x32x16_bf16 v[0:15], v[0:3], v[156:159], 0
	v_and_b32_e32 v22, 0xffff0000, v148
	v_lshlrev_b32_e32 v21, 16, v148
	v_mul_f32_e32 v22, v22, v22
	v_fmac_f32_e32 v22, v21, v21
	ds_read_b128 v[38:41], v250 offset:2560
	ds_read_b128 v[42:45], v250 offset:2048
	v_add_f32_e32 v37, v22, v20
	v_and_b32_e32 v47, 0xffff0000, v149
	v_mfma_f32_32x32x16_bf16 v[16:31], v[16:19], v[156:159], 0
	v_lshlrev_b32_e32 v46, 16, v149
	v_mul_f32_e32 v47, v47, v47
	v_fmac_f32_e32 v47, v46, v46
	v_add_f32_e32 v37, v47, v37
	v_and_b32_e32 v47, 0xffff0000, v150
	v_lshlrev_b32_e32 v46, 16, v150
	v_mul_f32_e32 v47, v47, v47
	s_waitcnt lgkmcnt(0)
	v_mfma_f32_32x32x16_bf16 v[0:15], v[42:45], v[152:155], v[0:15]
	v_fmac_f32_e32 v47, v46, v46
	v_and_b32_e32 v42, 0xffff0000, v151
	v_add_f32_e32 v37, v47, v37
	v_mul_f32_e32 v51, v42, v42
	ds_read_b128 v[42:45], v250 offset:4608
	ds_read_b128 v[46:49], v250 offset:4096
	v_lshlrev_b32_e32 v50, 16, v151
	v_fmac_f32_e32 v51, v50, v50
	v_mfma_f32_32x32x16_bf16 v[16:31], v[38:41], v[152:155], v[16:31]
	v_and_b32_e32 v39, 0xffff0000, v144
	v_lshlrev_b32_e32 v38, 16, v144
	v_mul_f32_e32 v39, v39, v39
	v_add_f32_e32 v37, v51, v37
	v_fmac_f32_e32 v39, v38, v38
	v_add_f32_e32 v37, v39, v37
	v_and_b32_e32 v39, 0xffff0000, v145
	s_waitcnt lgkmcnt(0)
	v_mfma_f32_32x32x16_bf16 v[0:15], v[46:49], v[148:151], v[0:15]
	v_lshlrev_b32_e32 v38, 16, v145
	v_mul_f32_e32 v39, v39, v39
	v_fmac_f32_e32 v39, v38, v38
	v_add_f32_e32 v37, v39, v37
	ds_read_b128 v[46:49], v250 offset:6656
	ds_read_b128 v[38:41], v250 offset:6144
	v_mfma_f32_32x32x16_bf16 v[16:31], v[42:45], v[148:151], v[16:31]
	v_and_b32_e32 v43, 0xffff0000, v146
	v_lshlrev_b32_e32 v42, 16, v146
	v_mul_f32_e32 v43, v43, v43
	v_fmac_f32_e32 v43, v42, v42
	v_add_f32_e32 v37, v43, v37
	v_and_b32_e32 v43, 0xffff0000, v147
	v_lshlrev_b32_e32 v42, 16, v147
	s_waitcnt lgkmcnt(0)
	v_mfma_f32_32x32x16_bf16 v[0:15], v[38:41], v[144:147], v[0:15]
	v_mul_f32_e32 v38, v43, v43
	v_fmac_f32_e32 v38, v42, v42
	v_add_f32_e32 v37, v38, v37
	v_mov_b32_e32 v38, v37
	s_nop 1
	v_permlane32_swap_b32_e32 v37, v38
	v_mfma_f32_32x32x16_bf16 v[16:31], v[46:49], v[144:147], v[16:31]
	s_nop 15
	s_nop 7
	s_cbranch_vccnz .LBB0_309
; __device__ __forceinline__ void cmask(f32x16&p0,f32x16&p1,int jb,int qrel,int hi){
;   const float NEG=-INFINITY; int kb=64*jb+4*hi;
;   #pragma unroll
;   for(int r=0;r<16;++r){int kv=kb+(r&3)+8*(r>>2); if(kv>qrel)p0[r]=NEG; if(kv+32>qrel)p1[r]=NEG;}
; }
	v_or_b32_e32 v39, 32, v245
	v_cmp_le_i32_e32 vcc, v39, v248
	v_or_b32_e32 v39, 33, v245
	s_nop 7
	v_cndmask_b32_e32 v16, v240, v16, vcc
	v_cmp_lt_i32_e32 vcc, v245, v248
	s_nop 1
	v_cndmask_b32_e32 v1, v240, v1, vcc
	v_cmp_le_i32_e32 vcc, v245, v248
	s_nop 1
	v_cndmask_b32_e32 v0, v240, v0, vcc
	v_cmp_le_i32_e32 vcc, v39, v248
	v_or_b32_e32 v39, 2, v245
	s_nop 0
	v_cndmask_b32_e32 v17, v240, v17, vcc
	v_cmp_le_i32_e32 vcc, v39, v248
	v_or_b32_e32 v39, 34, v245
	s_nop 0
	v_cndmask_b32_e32 v2, v240, v2, vcc
	v_cmp_le_i32_e32 vcc, v39, v248
	v_or_b32_e32 v39, 3, v245
	s_nop 0
	v_cndmask_b32_e32 v18, v240, v18, vcc
	v_cmp_le_i32_e32 vcc, v39, v248
	v_or_b32_e32 v39, 35, v245
	s_nop 0
	v_cndmask_b32_e32 v3, v240, v3, vcc
	v_cmp_le_i32_e32 vcc, v39, v248
	v_or_b32_e32 v39, 8, v245
	s_nop 0
	v_cndmask_b32_e32 v19, v240, v19, vcc
	v_cmp_le_i32_e32 vcc, v39, v248
	v_or_b32_e32 v39, 40, v245
	s_nop 0
	v_cndmask_b32_e32 v4, v240, v4, vcc
	v_cmp_le_i32_e32 vcc, v39, v248
	v_or_b32_e32 v39, 9, v245
	s_nop 0
	v_cndmask_b32_e32 v20, v240, v20, vcc
	v_cmp_le_i32_e32 vcc, v39, v248
	v_or_b32_e32 v39, 41, v245
	s_nop 0
	v_cndmask_b32_e32 v5, v240, v5, vcc
	v_cmp_le_i32_e32 vcc, v39, v248
	v_or_b32_e32 v39, 10, v245
	s_nop 0
	v_cndmask_b32_e32 v21, v240, v21, vcc
	v_cmp_le_i32_e32 vcc, v39, v248
	v_or_b32_e32 v39, 42, v245
	s_nop 0
	v_cndmask_b32_e32 v6, v240, v6, vcc
	v_cmp_le_i32_e32 vcc, v39, v248
	v_or_b32_e32 v39, 11, v245
	s_nop 0
	v_cndmask_b32_e32 v22, v240, v22, vcc
	v_cmp_le_i32_e32 vcc, v39, v248
	v_or_b32_e32 v39, 43, v245
	s_nop 0
	v_cndmask_b32_e32 v7, v240, v7, vcc
	v_cmp_le_i32_e32 vcc, v39, v248
	v_or_b32_e32 v39, 16, v245
	s_nop 0
	v_cndmask_b32_e32 v23, v240, v23, vcc
	v_cmp_le_i32_e32 vcc, v39, v248
	v_or_b32_e32 v39, 48, v245
	s_nop 0
	v_cndmask_b32_e32 v8, v240, v8, vcc
	v_cmp_le_i32_e32 vcc, v39, v248
	v_or_b32_e32 v39, 17, v245
	s_nop 0
	v_cndmask_b32_e32 v24, v240, v24, vcc
	v_cmp_le_i32_e32 vcc, v39, v248
	v_or_b32_e32 v39, 49, v245
	s_nop 0
	v_cndmask_b32_e32 v9, v240, v9, vcc
	v_cmp_le_i32_e32 vcc, v39, v248
	v_or_b32_e32 v39, 18, v245
	s_nop 0
	v_cndmask_b32_e32 v25, v240, v25, vcc
	v_cmp_le_i32_e32 vcc, v39, v248
	v_or_b32_e32 v39, 50, v245
	s_nop 0
	v_cndmask_b32_e32 v10, v240, v10, vcc
	v_cmp_le_i32_e32 vcc, v39, v248
	v_or_b32_e32 v39, 19, v245
	s_nop 0
	v_cndmask_b32_e32 v26, v240, v26, vcc
	v_cmp_le_i32_e32 vcc, v39, v248
	v_or_b32_e32 v39, 51, v245
	s_nop 0
	v_cndmask_b32_e32 v11, v240, v11, vcc
	v_cmp_le_i32_e32 vcc, v39, v248
	v_or_b32_e32 v39, 24, v245
	s_nop 0
	v_cndmask_b32_e32 v27, v240, v27, vcc
	v_cmp_le_i32_e32 vcc, v39, v248
	v_or_b32_e32 v39, 56, v245
	s_nop 0
	v_cndmask_b32_e32 v12, v240, v12, vcc
	v_cmp_le_i32_e32 vcc, v39, v248
	v_or_b32_e32 v39, 25, v245
	s_nop 0
	v_cndmask_b32_e32 v28, v240, v28, vcc
	v_cmp_le_i32_e32 vcc, v39, v248
	v_or_b32_e32 v39, 57, v245
	s_nop 0
	v_cndmask_b32_e32 v13, v240, v13, vcc
	v_cmp_le_i32_e32 vcc, v39, v248
	v_or_b32_e32 v39, 26, v245
	s_nop 0
	v_cndmask_b32_e32 v29, v240, v29, vcc
	v_cmp_le_i32_e32 vcc, v39, v248
	v_or_b32_e32 v39, 58, v245
	s_nop 0
	v_cndmask_b32_e32 v14, v240, v14, vcc
	v_cmp_le_i32_e32 vcc, v39, v248
	v_or_b32_e32 v39, 27, v245
	s_nop 0
	v_cndmask_b32_e32 v30, v240, v30, vcc
	v_cmp_le_i32_e32 vcc, v39, v248
	v_or_b32_e32 v39, 59, v245
	s_nop 0
	v_cndmask_b32_e32 v15, v240, v15, vcc
	v_cmp_le_i32_e32 vcc, v39, v248
	s_nop 1
	v_cndmask_b32_e32 v31, v240, v31, vcc

.LBB0_353:
	s_and_b32 s1, s95, 0x3fffffc0
	s_cmp_lg_u32 0, -1
	s_cselect_b32 s3, 0, 0
	s_lshl_b32 s1, s1, 2
	s_addk_i32 s3, 0x6000
	s_add_i32 s1, s1, 0
	v_add3_u32 v65, v251, s3, v249
	s_add_i32 s1, s1, 0x12000
	v_add_u32_e32 v66, s36, v252
	ds_read_b64_tr_b16 v[208:209], v66 offset:24576
	ds_read_b64_tr_b16 v[210:211], v66 offset:25088
	v_add_f32_e32 v67, v96, v97
	v_add_f32_e32 v67, v98, v67
	v_add_f32_e32 v67, v99, v67
	v_add_f32_e32 v67, v100, v67
	v_add_f32_e32 v67, v101, v67
	v_cvt_pk_bf16_f32 v172, v96, v97
	v_cvt_pk_bf16_f32 v173, v98, v99
	s_waitcnt lgkmcnt(9)
	v_mfma_f32_32x32x16_bf16 v[112:127], v[204:207], v[156:159], 0
	ds_read_b64_tr_b16 v[204:205], v66 offset:28672
	ds_read_b64_tr_b16 v[206:207], v66 offset:29184
	v_add_f32_e32 v67, v102, v67
	v_add_f32_e32 v67, v103, v67
	v_add_f32_e32 v67, v104, v67
	v_add_f32_e32 v67, v105, v67
	v_cvt_pk_bf16_f32 v174, v100, v101
	v_cvt_pk_bf16_f32 v175, v102, v103
	s_waitcnt lgkmcnt(10)
	v_mfma_f32_32x32x16_bf16 v[128:143], v[200:203], v[156:159], 0
	ds_read_b64_tr_b16 v[200:201], v66 offset:25600
	ds_read_b64_tr_b16 v[202:203], v66 offset:26112
	v_add_f32_e32 v67, v106, v67
	v_add_f32_e32 v67, v107, v67
	v_add_f32_e32 v67, v108, v67
	v_add_f32_e32 v67, v109, v67
	v_cvt_pk_bf16_f32 v168, v104, v105
	v_cvt_pk_bf16_f32 v169, v106, v107
	s_waitcnt lgkmcnt(11)
	v_mfma_f32_32x32x16_bf16 v[112:127], v[196:199], v[152:155], v[112:127]
	ds_read_b64_tr_b16 v[156:157], v66 offset:29696
	ds_read_b64_tr_b16 v[158:159], v66 offset:30208
	v_add_f32_e32 v67, v110, v67
	v_add_f32_e32 v67, v111, v67
	v_add_f32_e32 v67, v80, v67
	v_add_f32_e32 v67, v81, v67
	v_cvt_pk_bf16_f32 v170, v108, v109
	v_cvt_pk_bf16_f32 v171, v110, v111
	s_waitcnt lgkmcnt(12)
	v_mfma_f32_32x32x16_bf16 v[128:143], v[192:195], v[152:155], v[128:143]
	ds_read_b64_tr_b16 v[152:153], v66 offset:26624
	ds_read_b64_tr_b16 v[154:155], v66 offset:27136
	v_add_f32_e32 v67, v82, v67
	v_add_f32_e32 v67, v83, v67
	v_add_f32_e32 v67, v84, v67
	v_add_f32_e32 v67, v85, v67
	v_cvt_pk_bf16_f32 v164, v80, v81
	v_cvt_pk_bf16_f32 v165, v82, v83
	s_waitcnt lgkmcnt(13)
	v_mfma_f32_32x32x16_bf16 v[112:127], v[188:191], v[148:151], v[112:127]
	ds_read_b64_tr_b16 v[106:107], v66 offset:30720
	ds_read_b64_tr_b16 v[108:109], v66 offset:31232
	v_add_f32_e32 v67, v86, v67
	v_add_f32_e32 v67, v87, v67
	v_add_f32_e32 v67, v88, v67
	v_add_f32_e32 v67, v89, v67
	v_cvt_pk_bf16_f32 v166, v84, v85
	v_cvt_pk_bf16_f32 v167, v86, v87
	s_waitcnt lgkmcnt(14)
	v_mfma_f32_32x32x16_bf16 v[128:143], v[184:187], v[148:151], v[128:143]
	ds_read_b64_tr_b16 v[102:103], v66 offset:27648
	ds_read_b64_tr_b16 v[104:105], v66 offset:28160
	v_add_f32_e32 v67, v90, v67
	v_add_f32_e32 v67, v91, v67
	v_add_f32_e32 v67, v92, v67
	v_add_f32_e32 v67, v93, v67
	v_cvt_pk_bf16_f32 v160, v88, v89
	v_cvt_pk_bf16_f32 v161, v90, v91
	s_waitcnt lgkmcnt(14)
	v_mfma_f32_32x32x16_bf16 v[112:127], v[180:183], v[144:147], v[112:127]
	ds_read_b64_tr_b16 v[98:99], v66 offset:31744
	ds_read_b64_tr_b16 v[100:101], v66 offset:32256
	v_add_f32_e32 v67, v94, v67
	v_add_f32_e32 v67, v95, v67
	v_add_f32_e32 v148, 0, v67
	v_cvt_pk_bf16_f32 v162, v92, v93
	v_cvt_pk_bf16_f32 v163, v94, v95
	v_mfma_f32_32x32x16_bf16 v[128:143], v[176:179], v[144:147], v[128:143]
	v_or_b32_e32 v68, 0xe0, v245
	v_or_b32_e32 v67, 0xc0, v245
	v_cmp_le_i32_e32 vcc, v68, v248
	v_or_b32_e32 v68, 0xe1, v245
	v_or_b32_e32 v69, 0xc3, v245
	s_nop 6
	v_cndmask_b32_e32 v144, v240, v128, vcc
	v_cmp_lt_i32_e32 vcc, v67, v248
	v_or_b32_e32 v70, 0xc8, v245
	v_or_b32_e32 v71, 0xc9, v245
	v_cndmask_b32_e32 v83, v240, v113, vcc
	v_cmp_le_i32_e32 vcc, v67, v248
	v_or_b32_e32 v72, 0xca, v245
	v_or_b32_e32 v73, 0xcb, v245
	v_cndmask_b32_e32 v67, v240, v112, vcc
	v_cmp_le_i32_e32 vcc, v68, v248
	v_or_b32_e32 v68, 0xc2, v245
	v_or_b32_e32 v74, 0xd0, v245
	v_cndmask_b32_e32 v145, v240, v129, vcc
	v_cmp_le_i32_e32 vcc, v68, v248
	v_or_b32_e32 v68, 0xe2, v245
	v_or_b32_e32 v75, 0xd1, v245
	v_cndmask_b32_e32 v84, v240, v114, vcc
	v_cmp_le_i32_e32 vcc, v68, v248
	v_or_b32_e32 v76, 0xd2, v245
	v_or_b32_e32 v77, 0xd3, v245
	v_cndmask_b32_e32 v68, v240, v130, vcc
	v_cmp_le_i32_e32 vcc, v69, v248
	v_or_b32_e32 v69, 0xe3, v245
	v_or_b32_e32 v78, 0xd8, v245
	v_cndmask_b32_e32 v85, v240, v115, vcc
	v_cmp_le_i32_e32 vcc, v69, v248
	v_or_b32_e32 v79, 0xd9, v245
	v_or_b32_e32 v80, 0xda, v245
	v_cndmask_b32_e32 v69, v240, v131, vcc
	v_cmp_le_i32_e32 vcc, v70, v248
	v_or_b32_e32 v70, 0xe8, v245
	v_or_b32_e32 v81, 0xdb, v245
	v_cndmask_b32_e32 v86, v240, v116, vcc
	v_cmp_le_i32_e32 vcc, v70, v248
	s_nop 1
	v_cndmask_b32_e32 v70, v240, v132, vcc
	v_cmp_le_i32_e32 vcc, v71, v248
	v_or_b32_e32 v71, 0xe9, v245
	s_nop 0
	v_cndmask_b32_e32 v87, v240, v117, vcc
	v_cmp_le_i32_e32 vcc, v71, v248
	s_nop 1
	v_cndmask_b32_e32 v71, v240, v133, vcc
	v_cmp_le_i32_e32 vcc, v72, v248
	v_or_b32_e32 v72, 0xea, v245
	s_nop 0
	v_cndmask_b32_e32 v88, v240, v118, vcc
	v_cmp_le_i32_e32 vcc, v72, v248
	s_nop 1
	v_cndmask_b32_e32 v72, v240, v134, vcc
	v_cmp_le_i32_e32 vcc, v73, v248
	v_or_b32_e32 v73, 0xeb, v245
	s_nop 0
	v_cndmask_b32_e32 v89, v240, v119, vcc
	v_cmp_le_i32_e32 vcc, v73, v248
	s_nop 1
	v_cndmask_b32_e32 v73, v240, v135, vcc
	v_cmp_le_i32_e32 vcc, v74, v248
	v_or_b32_e32 v74, 0xf0, v245
	s_nop 0
	v_cndmask_b32_e32 v90, v240, v120, vcc
	v_cmp_le_i32_e32 vcc, v74, v248
	s_nop 1
	v_cndmask_b32_e32 v74, v240, v136, vcc
	v_cmp_le_i32_e32 vcc, v75, v248
	v_or_b32_e32 v75, 0xf1, v245
	s_nop 0
	v_cndmask_b32_e32 v91, v240, v121, vcc
	v_cmp_le_i32_e32 vcc, v75, v248
	s_nop 1
	v_cndmask_b32_e32 v75, v240, v137, vcc
	v_cmp_le_i32_e32 vcc, v76, v248
	v_or_b32_e32 v76, 0xf2, v245
	s_nop 0
	v_cndmask_b32_e32 v92, v240, v122, vcc
	v_cmp_le_i32_e32 vcc, v76, v248
	s_nop 1
	v_cndmask_b32_e32 v76, v240, v138, vcc
	v_cmp_le_i32_e32 vcc, v77, v248
	v_or_b32_e32 v77, 0xf3, v245
	s_nop 0
	v_cndmask_b32_e32 v93, v240, v123, vcc
	v_cmp_le_i32_e32 vcc, v77, v248
	s_nop 1
	v_cndmask_b32_e32 v77, v240, v139, vcc
	v_cmp_le_i32_e32 vcc, v78, v248
	v_or_b32_e32 v78, 0xf8, v245
	s_nop 0
	v_cndmask_b32_e32 v94, v240, v124, vcc
	v_cmp_le_i32_e32 vcc, v78, v248
	s_nop 1
	v_cndmask_b32_e32 v78, v240, v140, vcc
	v_cmp_le_i32_e32 vcc, v79, v248
	v_or_b32_e32 v79, 0xf9, v245
	s_nop 0
	v_cndmask_b32_e32 v95, v240, v125, vcc
	v_cmp_le_i32_e32 vcc, v79, v248
	s_nop 1
	v_cndmask_b32_e32 v79, v240, v141, vcc
	v_cmp_le_i32_e32 vcc, v80, v248
	v_or_b32_e32 v80, 0xfa, v245
	s_nop 0
	v_cndmask_b32_e32 v96, v240, v126, vcc
	v_cmp_le_i32_e32 vcc, v80, v248
	s_nop 1
	v_cndmask_b32_e32 v80, v240, v142, vcc
	v_cmp_le_i32_e32 vcc, v81, v248
	v_or_b32_e32 v81, 0xfb, v245
	s_nop 0
	v_cndmask_b32_e32 v97, v240, v127, vcc
	v_cmp_le_i32_e32 vcc, v81, v248
	s_nop 1
	v_cndmask_b32_e32 v81, v240, v143, vcc
	s_waitcnt lgkmcnt(14)
; #define SBAR() __builtin_amdgcn_sched_barrier(0)
; #define WAIT_BAR(N) asm volatile("s_waitcnt vmcnt(" #N ") lgkmcnt(0)\n\ts_barrier":::"memory")
;   #define RESC() do{ if(resc){ asm volatile("s_waitcnt lgkmcnt(0)":::"memory"); \
;       _Pragma("unroll") for(int d_=0;d_<2;++d_) _Pragma("unroll") for(int r=0;r<16;++r){const float f_=wsf[crow(r,hi)];o[d_][r]*=f_;o2[d_][r]*=f_;} } }while(0)
;   #define ROT() do{sl_prev=sl_cur;sl_cur=sl_next;sl_next=(sl_next==(NSLOT-1)*SLOTB)?0:sl_next+SLOTB;}while(0)
;   #define PKW(P,B) cvtpk_s(P[B],P[B+1])
;   #define ENDW(tt) do{ if((tt)+3<NT){WAIT_BAR(3);} else if((tt)+2<NT){WAIT_BAR(2);} else {WAIT_BAR(0);} }while(0)
; template<int THRL> __device__ __forceinline__ void attn_unit(int b,int h,int qb,unsigned char*wsb,char*shm,float kmax,const int CMB,float lam){
;     ...
;   int t=1;
;     ...
;   for(;t+5<NT;t+=2){
;     STEP(pB0,pB1,pA0,pA1,t,true,true,true);     WAIT_BAR(3); RESC(); ROT();
;     STEP(pA0,pA1,pB0,pB1,t+1,true,true,true);   WAIT_BAR(3); RESC(); ROT();
;   }
;     ...
;   for(;t+1<NT;t+=2){
;     STEP(pB0,pB1,pA0,pA1,t,(t+3<NT),(t+1<NT),(t+1<NT));       ENDW(t);   RESC(); ROT();
;     STEP(pA0,pA1,pB0,pB1,t+1,(t+4<NT),(t+2<NT),(t+2<NT));     ENDW(t+1); RESC(); ROT();
;   }
;   STEP(pB0,pB1,pA0,pA1,NT-1,false,false,false); RESC();
;   { float sacc=pB0[0]+pB0[1]; _Pragma("unroll") for(int r=2;r<16;++r)sacc+=pB0[r]; _Pragma("unroll") for(int r=0;r<16;++r)sacc+=pB1[r]; l_reg+=sacc;
;     pw0=(u32x4){PKW(pB0,0),PKW(pB0,2),PKW(pB0,4),PKW(pB0,6)};pw1=(u32x4){PKW(pB0,8),PKW(pB0,10),PKW(pB0,12),PKW(pB0,14)};pw2=(u32x4){PKW(pB1,0),PKW(pB1,2),PKW(pB1,4),PKW(pB1,6)};pw3=(u32x4){PKW(pB1,8),PKW(pB1,10),PKW(pB1,12),PKW(pB1,14)};
;     SBAR(); pv(o,vb0+sl_cur,PAF(0),PAF(1),PAF(2),PAF(3)); pv(o2,vb0+(LDS_V2-LDS_V)+sl_cur,PAF(0),PAF(1),PAF(2),PAF(3)); }
	v_mfma_f32_32x32x16_bf16 v[32:47], v[172:175], v[208:211], v[32:47]
	v_sub_f32_e32 v67, v67, v247
	v_exp_f32_e32 v82, v67
	v_sub_f32_e32 v67, v83, v247
	v_exp_f32_e32 v83, v67
	ds_read_b64_tr_b16 v[110:111], v66 offset:49152
	ds_read_b64_tr_b16 v[112:113], v66 offset:49664
	s_waitcnt lgkmcnt(14)
	v_mfma_f32_32x32x16_bf16 v[48:63], v[172:175], v[204:207], v[48:63]
	v_sub_f32_e32 v67, v84, v247
	v_exp_f32_e32 v84, v67
	v_sub_f32_e32 v67, v85, v247
	v_exp_f32_e32 v85, v67
	ds_read_b64_tr_b16 v[114:115], v66 offset:53248
	ds_read_b64_tr_b16 v[116:117], v66 offset:53760
	s_waitcnt lgkmcnt(14)
	v_mfma_f32_32x32x16_bf16 v[32:47], v[168:171], v[200:203], v[32:47]
	v_sub_f32_e32 v67, v86, v247
	v_exp_f32_e32 v86, v67
	v_sub_f32_e32 v67, v87, v247
	v_exp_f32_e32 v87, v67
	ds_read_b64_tr_b16 v[118:119], v66 offset:50176
	ds_read_b64_tr_b16 v[120:121], v66 offset:50688
	s_waitcnt lgkmcnt(14)
	v_mfma_f32_32x32x16_bf16 v[48:63], v[168:171], v[156:159], v[48:63]
	v_sub_f32_e32 v67, v88, v247
	v_exp_f32_e32 v88, v67
	v_sub_f32_e32 v67, v89, v247
	v_exp_f32_e32 v89, v67
	ds_read_b64_tr_b16 v[122:123], v66 offset:54272
	ds_read_b64_tr_b16 v[124:125], v66 offset:54784
	s_waitcnt lgkmcnt(14)
	v_mfma_f32_32x32x16_bf16 v[32:47], v[164:167], v[152:155], v[32:47]
	v_sub_f32_e32 v67, v90, v247
	v_exp_f32_e32 v90, v67
	v_sub_f32_e32 v67, v91, v247
	v_exp_f32_e32 v91, v67
	ds_read_b64_tr_b16 v[126:127], v66 offset:51200
	ds_read_b64_tr_b16 v[128:129], v66 offset:51712
	s_waitcnt lgkmcnt(14)
	v_mfma_f32_32x32x16_bf16 v[48:63], v[164:167], v[106:109], v[48:63]
	v_sub_f32_e32 v67, v92, v247
	v_exp_f32_e32 v92, v67
	v_sub_f32_e32 v67, v93, v247
	v_exp_f32_e32 v93, v67
	ds_read_b64_tr_b16 v[106:107], v66 offset:55296
	ds_read_b64_tr_b16 v[108:109], v66 offset:55808
	s_waitcnt lgkmcnt(14)
	v_mfma_f32_32x32x16_bf16 v[32:47], v[160:163], v[102:105], v[32:47]
	v_sub_f32_e32 v67, v94, v247
	v_exp_f32_e32 v94, v67
	v_sub_f32_e32 v67, v95, v247
	v_exp_f32_e32 v95, v67
	ds_read_b64_tr_b16 v[102:103], v66 offset:52224
	ds_read_b64_tr_b16 v[104:105], v66 offset:52736
	s_waitcnt lgkmcnt(14)
	v_mfma_f32_32x32x16_bf16 v[48:63], v[160:163], v[98:101], v[48:63]
	v_sub_f32_e32 v67, v96, v247
	v_exp_f32_e32 v96, v67
	v_sub_f32_e32 v67, v97, v247
	v_exp_f32_e32 v97, v67
	ds_read_b64_tr_b16 v[98:99], v66 offset:56320
	ds_read_b64_tr_b16 v[100:101], v66 offset:56832
	s_waitcnt lgkmcnt(14)
	v_mfma_f32_32x32x16_bf16 v[0:15], v[172:175], v[110:113], v[0:15]
	v_sub_f32_e32 v66, v144, v247
	v_sub_f32_e32 v67, v145, v247
	v_exp_f32_e32 v66, v66
	v_exp_f32_e32 v67, v67
	s_waitcnt lgkmcnt(12)
	v_mfma_f32_32x32x16_bf16 v[16:31], v[172:175], v[114:117], v[16:31]
	v_sub_f32_e32 v68, v68, v247
	v_sub_f32_e32 v69, v69, v247
	v_exp_f32_e32 v68, v68
	v_exp_f32_e32 v69, v69
	s_waitcnt lgkmcnt(10)
	v_mfma_f32_32x32x16_bf16 v[0:15], v[168:171], v[118:121], v[0:15]
	v_sub_f32_e32 v70, v70, v247
	v_sub_f32_e32 v71, v71, v247
	v_exp_f32_e32 v70, v70
	v_exp_f32_e32 v71, v71
	s_waitcnt lgkmcnt(8)
	v_mfma_f32_32x32x16_bf16 v[16:31], v[168:171], v[122:125], v[16:31]
	v_sub_f32_e32 v72, v72, v247
	v_sub_f32_e32 v73, v73, v247
	v_exp_f32_e32 v72, v72
	v_exp_f32_e32 v73, v73
	s_waitcnt lgkmcnt(6)
	v_mfma_f32_32x32x16_bf16 v[0:15], v[164:167], v[126:129], v[0:15]
	v_sub_f32_e32 v74, v74, v247
	v_sub_f32_e32 v75, v75, v247
	v_exp_f32_e32 v74, v74
	v_exp_f32_e32 v75, v75
	s_waitcnt lgkmcnt(4)
	v_mfma_f32_32x32x16_bf16 v[16:31], v[164:167], v[106:109], v[16:31]
	v_sub_f32_e32 v76, v76, v247
	v_sub_f32_e32 v77, v77, v247
	v_exp_f32_e32 v76, v76
	v_exp_f32_e32 v77, v77
	s_waitcnt lgkmcnt(2)
	v_mfma_f32_32x32x16_bf16 v[0:15], v[160:163], v[102:105], v[0:15]
	v_sub_f32_e32 v78, v78, v247
	v_sub_f32_e32 v79, v79, v247
	v_exp_f32_e32 v78, v78
	v_exp_f32_e32 v79, v79
	s_waitcnt lgkmcnt(0)
	v_mfma_f32_32x32x16_bf16 v[16:31], v[160:163], v[98:101], v[16:31]
	v_sub_f32_e32 v80, v80, v247
	v_sub_f32_e32 v81, v81, v247
	v_exp_f32_e32 v80, v80
	v_exp_f32_e32 v81, v81
	v_add_f32_e32 v98, v82, v83
	v_add_f32_e32 v98, v84, v98
	v_add_f32_e32 v98, v85, v98
	v_add_f32_e32 v98, v86, v98
	v_add_f32_e32 v98, v87, v98
	v_add_f32_e32 v98, v88, v98
	v_add_f32_e32 v98, v89, v98
	v_add_f32_e32 v98, v90, v98
	v_add_f32_e32 v98, v91, v98
	v_add_f32_e32 v98, v92, v98
	v_add_f32_e32 v98, v93, v98
	v_add_f32_e32 v98, v94, v98
	v_add_f32_e32 v98, v95, v98
	v_add_f32_e32 v98, v96, v98
	v_add_f32_e32 v98, v97, v98
	v_add_f32_e32 v98, v98, v66
	v_add_f32_e32 v98, v67, v98
	v_add_f32_e32 v98, v68, v98
	v_add_f32_e32 v98, v69, v98
	v_add_f32_e32 v98, v70, v98
	v_add_f32_e32 v98, v71, v98
	v_add_f32_e32 v98, v72, v98
	v_add_f32_e32 v98, v73, v98
	v_add_f32_e32 v98, v74, v98
	v_add_f32_e32 v98, v75, v98
	v_add_f32_e32 v98, v76, v98
	v_add_f32_e32 v98, v77, v98
	v_add_f32_e32 v98, v78, v98
	v_add_f32_e32 v98, v79, v98
	v_add_f32_e32 v98, v80, v98
	v_add_f32_e32 v98, v81, v98
	v_add_f32_e32 v64, v64, v148
	v_add_f32_e32 v64, v64, v98
	v_cvt_pk_bf16_f32 v82, v82, v83
	v_cvt_pk_bf16_f32 v83, v84, v85
	v_cvt_pk_bf16_f32 v84, v86, v87
	v_cvt_pk_bf16_f32 v85, v88, v89
	v_cvt_pk_bf16_f32 v86, v90, v91
	v_cvt_pk_bf16_f32 v87, v92, v93
	v_cvt_pk_bf16_f32 v88, v94, v95
	v_cvt_pk_bf16_f32 v89, v96, v97
	v_cvt_pk_bf16_f32 v66, v66, v67
	v_cvt_pk_bf16_f32 v67, v68, v69
	v_cvt_pk_bf16_f32 v68, v70, v71
	v_cvt_pk_bf16_f32 v69, v72, v73
	v_cvt_pk_bf16_f32 v70, v74, v75
	v_cvt_pk_bf16_f32 v71, v76, v77
	v_cvt_pk_bf16_f32 v72, v78, v79
	v_cvt_pk_bf16_f32 v73, v80, v81
	v_add3_u32 v65, v65, v246, s42
	ds_read_b64_tr_b16 v[74:75],v65 offset:0
	ds_read_b64_tr_b16 v[76:77],v65 offset:512
	ds_read_b64_tr_b16 v[78:79],v65 offset:1024
	ds_read_b64_tr_b16 v[80:81],v65 offset:1536
	ds_read_b64_tr_b16 v[90:91],v65 offset:2048
	ds_read_b64_tr_b16 v[92:93],v65 offset:2560
	ds_read_b64_tr_b16 v[94:95],v65 offset:3072
	ds_read_b64_tr_b16 v[96:97],v65 offset:3584
	s_waitcnt lgkmcnt(0)
; __device__ __forceinline__ int crow(int r,int hi){return (r&3)+8*(r>>2)+4*hi;}
; #define SBAR() __builtin_amdgcn_sched_barrier(0)
; template<int THRL> __device__ __forceinline__ void attn_unit(int b,int h,int qb,unsigned char*wsb,char*shm,float kmax,const int CMB,float lam){
;     ...
;     SBAR(); pv(o,vb0+sl_cur,PAF(0),PAF(1),PAF(2),PAF(3)); pv(o2,vb0+(LDS_V2-LDS_V)+sl_cur,PAF(0),PAF(1),PAF(2),PAF(3)); }
;     ...
;   {auto rr=__builtin_amdgcn_permlane32_swap(__float_as_uint(l_reg),__float_as_uint(l_reg),false,false);l_reg=__uint_as_float(rr[0])+__uint_as_float(rr[1]);}
;   if(hi==0)wsf[32+r32]=l_reg;asm volatile("s_waitcnt lgkmcnt(0)":::"memory");
;   float rli[16];
;   #pragma unroll
;   for(int r=0;r<16;++r)rli[r]=__builtin_amdgcn_rcpf(wsf[32+crow(r,hi)]);
;   bf16*O,*O2,*YA; const float*sw; { unsigned char*w_=wsb; asm volatile("":"+s"(w_)); O=(bf16*)(w_+AWS_OLO); O2=(bf16*)(w_+AWS_OHI); YA=(bf16*)(w_+AWS_YA); sw=(const float*)(w_+AWS_SW); }
;   u32x4 mine[2][4];
;   #pragma unroll
;   for(int ob=0;ob<2;++ob){ bf16*Ow=(ob?O2:O)+(rowbase+q0+wid*QBLK)*DM+h*D;
;     bf16*stg=(bf16*)(shm+LDS_OST)+wid*2048;
;     #pragma unroll
;     for(int r=0;r<16;++r){const int orow=crow(r,hi);
;       #pragma unroll
;       for(int d0=0;d0<2;++d0)stg[orow*64+d0*32+r32]=__float2bfloat16((ob?o2[d0][r]:o[d0][r])*rli[r]);}
;     asm volatile("s_waitcnt lgkmcnt(0)":::"memory");
;     #pragma unroll
;     for(int i=0;i<4;++i){const int row=i*8+(lane>>3),ch=lane&7; const u32x4 v=*(const u32x4*)(stg+row*64+ch*8); if(CMB==0){ATTN_STORE16(Ow+(long)row*DM+ch*8,v);} else mine[ob][i]=v;}
	s_nop 0
	v_mfma_f32_32x32x16_bf16 v[32:47], v[82:85], v[74:77], v[32:47]
	ds_read_b64_tr_b16 v[74:75],v65 offset:4096
	ds_read_b64_tr_b16 v[76:77],v65 offset:4608
	v_mfma_f32_32x32x16_bf16 v[32:47], v[86:89], v[78:81], v[32:47]
	ds_read_b64_tr_b16 v[78:79],v65 offset:5120
	ds_read_b64_tr_b16 v[80:81],v65 offset:5632
	v_mfma_f32_32x32x16_bf16 v[32:47], v[66:69], v[90:93], v[32:47]
	ds_read_b64_tr_b16 v[90:91],v65 offset:6144
	ds_read_b64_tr_b16 v[92:93],v65 offset:6656
	ds_read_b64_tr_b16 v[98:99],v65 offset:7168
	ds_read_b64_tr_b16 v[100:101],v65 offset:7680
	s_waitcnt lgkmcnt(0)
	v_mfma_f32_32x32x16_bf16 v[32:47], v[70:73], v[94:97], v[32:47]
	v_mfma_f32_32x32x16_bf16 v[48:63], v[82:85], v[74:77], v[48:63]
	v_add_u32_e32 v65, 0x6000, v65
	ds_read_b64_tr_b16 v[74:75],v65 offset:0
	ds_read_b64_tr_b16 v[76:77],v65 offset:512
	v_mfma_f32_32x32x16_bf16 v[48:63], v[86:89], v[78:81], v[48:63]
	ds_read_b64_tr_b16 v[78:79],v65 offset:1024
	ds_read_b64_tr_b16 v[80:81],v65 offset:1536
	v_mfma_f32_32x32x16_bf16 v[48:63], v[66:69], v[90:93], v[48:63]
	ds_read_b64_tr_b16 v[90:91],v65 offset:2048
	ds_read_b64_tr_b16 v[92:93],v65 offset:2560
	ds_read_b64_tr_b16 v[94:95],v65 offset:3072
	ds_read_b64_tr_b16 v[96:97],v65 offset:3584
	s_waitcnt lgkmcnt(0)
	v_mfma_f32_32x32x16_bf16 v[48:63], v[70:73], v[98:101], v[48:63]
	v_mfma_f32_32x32x16_bf16 v[0:15], v[82:85], v[74:77], v[0:15]
	ds_read_b64_tr_b16 v[74:75],v65 offset:4096
	ds_read_b64_tr_b16 v[76:77],v65 offset:4608
	v_mfma_f32_32x32x16_bf16 v[0:15], v[86:89], v[78:81], v[0:15]
	ds_read_b64_tr_b16 v[78:79],v65 offset:5120
	ds_read_b64_tr_b16 v[80:81],v65 offset:5632
	v_mfma_f32_32x32x16_bf16 v[0:15], v[66:69], v[90:93], v[0:15]
	ds_read_b64_tr_b16 v[90:91],v65 offset:6144
	ds_read_b64_tr_b16 v[92:93],v65 offset:6656
	ds_read_b64_tr_b16 v[98:99],v65 offset:7168
	ds_read_b64_tr_b16 v[100:101],v65 offset:7680
	s_waitcnt lgkmcnt(0)
	v_mfma_f32_32x32x16_bf16 v[0:15], v[70:73], v[94:97], v[0:15]
	v_mfma_f32_32x32x16_bf16 v[16:31], v[82:85], v[74:77], v[16:31]
	v_mov_b32_e32 v65, v64
	s_nop 1
	v_permlane32_swap_b32_e32 v64, v65
	v_cmp_gt_u32_e32 vcc, 32, v241
	v_mfma_f32_32x32x16_bf16 v[16:31], v[86:89], v[78:81], v[16:31]
	v_mfma_f32_32x32x16_bf16 v[16:31], v[66:69], v[90:93], v[16:31]
	v_mfma_f32_32x32x16_bf16 v[16:31], v[70:73], v[98:101], v[16:31]
	s_and_saveexec_b64 s[4:5], vcc
	v_add_f32_e32 v64, v64, v65
	v_lshl_add_u32 v65, v243, 2, s1
	ds_write_b32 v65, v64 offset:128
	s_or_b64 exec, exec, s[4:5]
	s_waitcnt lgkmcnt(0)
	v_lshl_add_u32 v72, v245, 2, s1
	ds_read_b128 v[64:67], v72 offset:128
	ds_read_b128 v[68:71], v72 offset:160
	s_lshl_b32 s1, s94, 12
	s_add_i32 s1, s1, 0
	ds_read_b128 v[82:85], v72 offset:224
	s_waitcnt lgkmcnt(2)
	v_rcp_f32_e32 v81, v64
	v_rcp_f32_e32 v80, v65
	v_rcp_f32_e32 v79, v66
	v_rcp_f32_e32 v78, v67
	ds_read_b128 v[64:67], v72 offset:192
	s_add_i32 s1, s1, 0x12800
	s_waitcnt lgkmcnt(2)
	v_rcp_f32_e32 v76, v69
	v_lshl_add_u32 v69, v243, 1, s1
	v_mul_f32_e32 v32, v32, v81
	s_waitcnt lgkmcnt(0)
	v_rcp_f32_e32 v72, v65
	v_rcp_f32_e32 v65, v84
	v_lshlrev_b32_e32 v84, 9, v242
	s_mov_b64 s[64:65], s[8:9]
	v_add_u32_e32 v69, v69, v84
	v_cvt_pk_bf16_f32 v32, v32, s0
	ds_write_b16 v69, v32
	v_mul_f32_e32 v32, v48, v81
	v_cvt_pk_bf16_f32 v32, v32, s0
	ds_write_b16 v69, v32 offset:64
	v_mul_f32_e32 v32, v33, v80
	v_cvt_pk_bf16_f32 v32, v32, s0
	ds_write_b16 v69, v32 offset:128
	v_mul_f32_e32 v32, v49, v80
	v_cvt_pk_bf16_f32 v32, v32, s0
	ds_write_b16 v69, v32 offset:192
	v_mul_f32_e32 v32, v34, v79
	v_cvt_pk_bf16_f32 v32, v32, s0
	ds_write_b16 v69, v32 offset:256
	v_mul_f32_e32 v32, v50, v79
	v_cvt_pk_bf16_f32 v32, v32, s0
	v_rcp_f32_e32 v77, v68
	ds_write_b16 v69, v32 offset:320
	v_mul_f32_e32 v32, v35, v78
	v_cvt_pk_bf16_f32 v32, v32, s0
	ds_write_b16 v69, v32 offset:384
	v_mul_f32_e32 v32, v51, v78
	v_cvt_pk_bf16_f32 v32, v32, s0
	ds_write_b16 v69, v32 offset:448
	v_mul_f32_e32 v32, v36, v77
	v_cvt_pk_bf16_f32 v32, v32, s0
	ds_write_b16 v69, v32 offset:1024
	v_mul_f32_e32 v32, v52, v77
	v_cvt_pk_bf16_f32 v32, v32, s0
	v_rcp_f32_e32 v75, v70
	ds_write_b16 v69, v32 offset:1088
	v_mul_f32_e32 v32, v37, v76
	v_cvt_pk_bf16_f32 v32, v32, s0
	ds_write_b16 v69, v32 offset:1152
	v_mul_f32_e32 v32, v53, v76
	v_cvt_pk_bf16_f32 v32, v32, s0
	v_rcp_f32_e32 v73, v71
	ds_write_b16 v69, v32 offset:1216
	v_mul_f32_e32 v32, v38, v75
	v_cvt_pk_bf16_f32 v32, v32, s0
	ds_write_b16 v69, v32 offset:1280
	v_mul_f32_e32 v32, v54, v75
	v_cvt_pk_bf16_f32 v32, v32, s0
	v_rcp_f32_e32 v74, v64
	ds_write_b16 v69, v32 offset:1344
	v_mul_f32_e32 v32, v39, v73
	v_cvt_pk_bf16_f32 v32, v32, s0
	ds_write_b16 v69, v32 offset:1408
	v_mul_f32_e32 v32, v55, v73
	v_cvt_pk_bf16_f32 v32, v32, s0
	ds_write_b16 v69, v32 offset:1472
	v_mul_f32_e32 v32, v40, v74
	v_cvt_pk_bf16_f32 v32, v32, s0
	ds_write_b16 v69, v32 offset:2048
	v_mul_f32_e32 v32, v56, v74
	v_cvt_pk_bf16_f32 v32, v32, s0
	v_rcp_f32_e32 v71, v66
	ds_write_b16 v69, v32 offset:2112
	v_mul_f32_e32 v32, v41, v72
	v_cvt_pk_bf16_f32 v32, v32, s0
	ds_write_b16 v69, v32 offset:2176
	v_mul_f32_e32 v32, v57, v72
	v_cvt_pk_bf16_f32 v32, v32, s0
	v_rcp_f32_e32 v70, v67
	ds_write_b16 v69, v32 offset:2240
	v_mul_f32_e32 v32, v42, v71
	v_cvt_pk_bf16_f32 v32, v32, s0
	ds_write_b16 v69, v32 offset:2304
	v_mul_f32_e32 v32, v58, v71
	v_cvt_pk_bf16_f32 v32, v32, s0
	v_rcp_f32_e32 v68, v82
	ds_write_b16 v69, v32 offset:2368
	v_mul_f32_e32 v32, v43, v70
	v_cvt_pk_bf16_f32 v32, v32, s0
	ds_write_b16 v69, v32 offset:2432
	v_mul_f32_e32 v32, v59, v70
	v_cvt_pk_bf16_f32 v32, v32, s0
	v_rcp_f32_e32 v67, v83
	ds_write_b16 v69, v32 offset:2496
	v_mul_f32_e32 v32, v44, v68
	v_cvt_pk_bf16_f32 v32, v32, s0
	ds_write_b16 v69, v32 offset:3072
	v_mul_f32_e32 v32, v60, v68
	v_cvt_pk_bf16_f32 v32, v32, s0
	ds_write_b16 v69, v32 offset:3136
	v_mul_f32_e32 v32, v45, v67
	v_cvt_pk_bf16_f32 v32, v32, s0
	ds_write_b16 v69, v32 offset:3200
	v_mul_f32_e32 v32, v61, v67
	v_cvt_pk_bf16_f32 v32, v32, s0
	v_rcp_f32_e32 v64, v85
	ds_write_b16 v69, v32 offset:3264
	v_mul_f32_e32 v32, v46, v65
	v_cvt_pk_bf16_f32 v32, v32, s0
	ds_write_b16 v69, v32 offset:3328
	v_mul_f32_e32 v32, v62, v65
	v_cvt_pk_bf16_f32 v32, v32, s0
	ds_write_b16 v69, v32 offset:3392
	v_mul_f32_e32 v32, v47, v64
	v_cvt_pk_bf16_f32 v32, v32, s0
	v_and_b32_e32 v66, 56, v244
	ds_write_b16 v69, v32 offset:3456
	v_mul_f32_e32 v32, v63, v64
	v_lshrrev_b32_e32 v82, 3, v241
	v_lshlrev_b32_e32 v220, 1, v66
	s_lshl_b64 s[62:63], s[62:63], 1
	v_cvt_pk_bf16_f32 v32, v32, s0
	v_add_u32_e32 v83, s1, v220
	s_add_u32 s1, s64, s62
	ds_write_b16 v69, v32 offset:3520
	v_lshlrev_b32_e32 v32, 7, v82
	s_addc_u32 s3, s65, s63
	s_waitcnt lgkmcnt(0)
	v_add_u32_e32 v58, v83, v32
	s_add_u32 s1, s1, 0x30000000
	ds_read_b128 v[44:47], v58
	s_addc_u32 s3, s3, 0
	s_lshl_b32 s6, s93, 1
	s_add_u32 s4, s1, s6
	s_addc_u32 s5, s3, 0
	v_cndmask_b32_e64 v32, 0, 1, s[58:59]
	v_lshl_add_u64 v[56:57], s[4:5], 0, v[220:221]
	v_cmp_ne_u32_e64 s[4:5], 1, v32
	s_andn2_b64 vcc, exec, s[58:59]
	v_lshlrev_b32_e32 v48, 11, v82
	s_cbranch_vccnz .LBB0_357
; __device__ __forceinline__ int crow(int r,int hi){return (r&3)+8*(r>>2)+4*hi;}
; template<int THRL> __device__ __forceinline__ void attn_unit(int b,int h,int qb,unsigned char*wsb,char*shm,float kmax,const int CMB,float lam){
;     ...
;   for(int ob=0;ob<2;++ob){ bf16*Ow=(ob?O2:O)+(rowbase+q0+wid*QBLK)*DM+h*D;
;     bf16*stg=(bf16*)(shm+LDS_OST)+wid*2048;
;     #pragma unroll
;     for(int r=0;r<16;++r){const int orow=crow(r,hi);
;       #pragma unroll
;       for(int d0=0;d0<2;++d0)stg[orow*64+d0*32+r32]=__float2bfloat16((ob?o2[d0][r]:o[d0][r])*rli[r]);}
;     asm volatile("s_waitcnt lgkmcnt(0)":::"memory");
;     #pragma unroll
;     for(int i=0;i<4;++i){const int row=i*8+(lane>>3),ch=lane&7; const u32x4 v=*(const u32x4*)(stg+row*64+ch*8); if(CMB==0){ATTN_STORE16(Ow+(long)row*DM+ch*8,v);} else mine[ob][i]=v;}
;     asm volatile("s_waitcnt lgkmcnt(0)":::"memory"); }
	v_mov_b32_e32 v49, v221
	v_lshl_add_u64 v[32:33], v[56:57], 0, v[48:49]
	s_waitcnt lgkmcnt(0)
	global_store_dwordx4 v[32:33], v[44:47], off
.LBB0_357:
	v_or_b32_e32 v32, 8, v82
	v_lshlrev_b32_e32 v33, 7, v32
	v_add_u32_e32 v59, v83, v33
	ds_read_b128 v[40:43], v59
	s_and_b64 vcc, exec, s[4:5]
	v_lshlrev_b32_e32 v50, 11, v32
	s_cbranch_vccnz .LBB0_359
	v_mov_b32_e32 v51, v221
	v_lshl_add_u64 v[32:33], v[56:57], 0, v[50:51]
	s_waitcnt lgkmcnt(0)
	global_store_dwordx4 v[32:33], v[40:43], off
.LBB0_359:
	v_or_b32_e32 v32, 16, v82
	v_lshlrev_b32_e32 v33, 7, v32
	v_add_u32_e32 v60, v83, v33
	ds_read_b128 v[36:39], v60
	s_and_b64 vcc, exec, s[4:5]
	v_lshlrev_b32_e32 v52, 11, v32
	s_cbranch_vccnz .LBB0_361
	v_mov_b32_e32 v53, v221
	v_lshl_add_u64 v[32:33], v[56:57], 0, v[52:53]
	s_waitcnt lgkmcnt(0)
	global_store_dwordx4 v[32:33], v[36:39], off
.LBB0_361:
	v_or_b32_e32 v49, 24, v82
	v_lshlrev_b32_e32 v32, 7, v49
	v_add_u32_e32 v61, v83, v32
	ds_read_b128 v[32:35], v61
	s_and_b64 vcc, exec, s[4:5]
	v_lshlrev_b32_e32 v54, 11, v49
	s_cbranch_vccnz .LBB0_363
	v_mov_b32_e32 v55, v221
	v_lshl_add_u64 v[56:57], v[56:57], 0, v[54:55]
	s_waitcnt lgkmcnt(0)
	global_store_dwordx4 v[56:57], v[32:35], off
.LBB0_363:
	v_mul_f32_e32 v0, v0, v81
	v_cvt_pk_bf16_f32 v0, v0, s0
	s_waitcnt lgkmcnt(0)
	ds_write_b16 v69, v0
	v_mul_f32_e32 v0, v16, v81
	v_cvt_pk_bf16_f32 v0, v0, s0
	ds_write_b16 v69, v0 offset:64
	v_mul_f32_e32 v0, v1, v80
	v_cvt_pk_bf16_f32 v0, v0, s0
	ds_write_b16 v69, v0 offset:128
	v_mul_f32_e32 v0, v17, v80
	v_cvt_pk_bf16_f32 v0, v0, s0
	ds_write_b16 v69, v0 offset:192
	v_mul_f32_e32 v0, v2, v79
	v_cvt_pk_bf16_f32 v0, v0, s0
	ds_write_b16 v69, v0 offset:256
	v_mul_f32_e32 v0, v18, v79
	v_cvt_pk_bf16_f32 v0, v0, s0
	ds_write_b16 v69, v0 offset:320
	v_mul_f32_e32 v0, v3, v78
	v_cvt_pk_bf16_f32 v0, v0, s0
	ds_write_b16 v69, v0 offset:384
	v_mul_f32_e32 v0, v19, v78
	v_cvt_pk_bf16_f32 v0, v0, s0
	ds_write_b16 v69, v0 offset:448
	v_mul_f32_e32 v0, v4, v77
	v_cvt_pk_bf16_f32 v0, v0, s0
	ds_write_b16 v69, v0 offset:1024
	v_mul_f32_e32 v0, v20, v77
	v_cvt_pk_bf16_f32 v0, v0, s0
	ds_write_b16 v69, v0 offset:1088
	v_mul_f32_e32 v0, v5, v76
	v_cvt_pk_bf16_f32 v0, v0, s0
	ds_write_b16 v69, v0 offset:1152
	v_mul_f32_e32 v0, v21, v76
	v_cvt_pk_bf16_f32 v0, v0, s0
	ds_write_b16 v69, v0 offset:1216
	v_mul_f32_e32 v0, v6, v75
	v_cvt_pk_bf16_f32 v0, v0, s0
	ds_write_b16 v69, v0 offset:1280
	v_mul_f32_e32 v0, v22, v75
	v_cvt_pk_bf16_f32 v0, v0, s0
	ds_write_b16 v69, v0 offset:1344
	v_mul_f32_e32 v0, v7, v73
	v_cvt_pk_bf16_f32 v0, v0, s0
	ds_write_b16 v69, v0 offset:1408
	v_mul_f32_e32 v0, v23, v73
	v_cvt_pk_bf16_f32 v0, v0, s0
	ds_write_b16 v69, v0 offset:1472
	v_mul_f32_e32 v0, v8, v74
	v_cvt_pk_bf16_f32 v0, v0, s0
	ds_write_b16 v69, v0 offset:2048
	v_mul_f32_e32 v0, v24, v74
	v_cvt_pk_bf16_f32 v0, v0, s0
	ds_write_b16 v69, v0 offset:2112
	v_mul_f32_e32 v0, v9, v72
	v_cvt_pk_bf16_f32 v0, v0, s0
	ds_write_b16 v69, v0 offset:2176
	v_mul_f32_e32 v0, v25, v72
	v_cvt_pk_bf16_f32 v0, v0, s0
	ds_write_b16 v69, v0 offset:2240
	v_mul_f32_e32 v0, v10, v71
	v_cvt_pk_bf16_f32 v0, v0, s0
	ds_write_b16 v69, v0 offset:2304
	v_mul_f32_e32 v0, v26, v71
	v_cvt_pk_bf16_f32 v0, v0, s0
	ds_write_b16 v69, v0 offset:2368
	v_mul_f32_e32 v0, v11, v70
	v_cvt_pk_bf16_f32 v0, v0, s0
	ds_write_b16 v69, v0 offset:2432
	v_mul_f32_e32 v0, v27, v70
	v_cvt_pk_bf16_f32 v0, v0, s0
	ds_write_b16 v69, v0 offset:2496
	v_mul_f32_e32 v0, v12, v68
	v_cvt_pk_bf16_f32 v0, v0, s0
	ds_write_b16 v69, v0 offset:3072
	v_mul_f32_e32 v0, v28, v68
	v_cvt_pk_bf16_f32 v0, v0, s0
	ds_write_b16 v69, v0 offset:3136
	v_mul_f32_e32 v0, v13, v67
	v_cvt_pk_bf16_f32 v0, v0, s0
	ds_write_b16 v69, v0 offset:3200
	v_mul_f32_e32 v0, v29, v67
	v_cvt_pk_bf16_f32 v0, v0, s0
	ds_write_b16 v69, v0 offset:3264
	v_mul_f32_e32 v0, v14, v65
	v_cvt_pk_bf16_f32 v0, v0, s0
	ds_write_b16 v69, v0 offset:3328
	v_mul_f32_e32 v0, v30, v65
	v_cvt_pk_bf16_f32 v0, v0, s0
	ds_write_b16 v69, v0 offset:3392
	v_mul_f32_e32 v0, v15, v64
	v_cvt_pk_bf16_f32 v0, v0, s0
	ds_write_b16 v69, v0 offset:3456
	v_mul_f32_e32 v0, v31, v64
	v_cvt_pk_bf16_f32 v0, v0, s0
	s_add_u32 s33, s64, s62
	ds_write_b16 v69, v0 offset:3520
	s_addc_u32 s36, s65, s63
	s_waitcnt lgkmcnt(0)
	s_add_u32 s33, s33, 0x34000000
	ds_read_b128 v[4:7], v58
	s_addc_u32 s36, s36, 0
	s_add_u32 s42, s33, s6
	s_addc_u32 s43, s36, 0
	s_and_b64 vcc, exec, s[4:5]
	v_lshl_add_u64 v[8:9], s[42:43], 0, v[220:221]
	s_cbranch_vccnz .LBB0_367
	v_mov_b32_e32 v49, v221
	v_lshl_add_u64 v[0:1], v[8:9], 0, v[48:49]
	s_waitcnt lgkmcnt(0)
	global_store_dwordx4 v[0:1], v[4:7], off
	ds_read_b128 v[24:27], v59
	s_and_b64 vcc, exec, s[4:5]
	s_cbranch_vccz .LBB0_368

; template<int THRL> __device__ __forceinline__ void attn_unit(int b,int h,int qb,unsigned char*wsb,char*shm,float kmax,const int CMB,float lam){
;     ...
;     for(int i=0;i<4;++i){const int row=i*8+(lane>>3),ch=lane&7; const u32x4 v=*(const u32x4*)(stg+row*64+ch*8); if(CMB==0){ATTN_STORE16(Ow+(long)row*DM+ch*8,v);} else mine[ob][i]=v;}
;     asm volatile("s_waitcnt lgkmcnt(0)":::"memory"); }
.LBB0_366:
	v_mov_b32_e32 v53, v221
	v_lshl_add_u64 v[0:1], v[8:9], 0, v[52:53]
	s_waitcnt lgkmcnt(0)
	global_store_dwordx4 v[0:1], v[16:19], off
	ds_read_b128 v[0:3], v61
	s_and_b64 vcc, exec, s[4:5]
	s_cbranch_vccz .LBB0_370
	s_branch .LBB0_371

; template<int THRL> __device__ __forceinline__ void attn_unit(int b,int h,int qb,unsigned char*wsb,char*shm,float kmax,const int CMB,float lam){
;     ...
;     for(int i=0;i<4;++i){const int row=i*8+(lane>>3),ch=lane&7; const u32x4 v=*(const u32x4*)(stg+row*64+ch*8); if(CMB==0){ATTN_STORE16(Ow+(long)row*DM+ch*8,v);} else mine[ob][i]=v;}
;     asm volatile("s_waitcnt lgkmcnt(0)":::"memory"); }
.LBB0_368:
	v_mov_b32_e32 v51, v221
	v_lshl_add_u64 v[0:1], v[8:9], 0, v[50:51]
	s_waitcnt lgkmcnt(0)
	global_store_dwordx4 v[0:1], v[24:27], off
	ds_read_b128 v[16:19], v60
	s_and_b64 vcc, exec, s[4:5]
	s_cbranch_vccz .LBB0_366

; template<int THRL> __device__ __forceinline__ void attn_unit(int b,int h,int qb,unsigned char*wsb,char*shm,float kmax,const int CMB,float lam){
;     ...
;   if(CMB==1){
;     const int ch=lane&7; const bf16*P1lo=O+(rowbase+q0+wid*QBLK)*DM+(h-1)*D+ch*8,*P1hi=O2+(rowbase+q0+wid*QBLK)*DM+(h-1)*D+ch*8;
;     float swl[8],swh[8];
;     #pragma unroll
;     for(int e=0;e<8;++e){swl[e]=sw[ch*8+e];swh[e]=sw[64+ch*8+e];}
;     bf16*Yw=YA+(rowbase+q0+wid*QBLK)*(long)ya_pitch+(h>>1)*128+ch*8;
;     u32x4 p1[2][4];
;     #pragma unroll
;     for(int i=0;i<4;++i){const int row=i*8+(lane>>3); p1[0][i]=*(const u32x4*)(P1lo+(long)row*DM); p1[1][i]=*(const u32x4*)(P1hi+(long)row*DM);}
;     #pragma unroll
;     for(int i=0;i<4;++i){const int row=i*8+(lane>>3); float a_[16]; float ss=0.f;
;       #pragma unroll
;       for(int t=0;t<2;++t)
;         #pragma unroll
;         for(int e=0;e<4;++e){const unsigned w1=p1[t][i][e],w2=mine[t][i][e];
;           const float x0=__uint_as_float(w1<<16)-lam*__uint_as_float(w2<<16), x1=__uint_as_float(w1&0xffff0000u)-lam*__uint_as_float(w2&0xffff0000u);
;           a_[t*8+2*e]=x0;a_[t*8+2*e+1]=x1;ss+=x0*x0+x1*x1;}
;       ss+=__shfl_xor(ss,1);ss+=__shfl_xor(ss,2);ss+=__shfl_xor(ss,4);
.LBB0_370:
	v_mov_b32_e32 v55, v221
	v_lshl_add_u64 v[8:9], v[8:9], 0, v[54:55]
	s_waitcnt lgkmcnt(0)
	global_store_dwordx4 v[8:9], v[0:3], off
.LBB0_371:
	s_waitcnt lgkmcnt(0)
	s_andn2_b64 vcc, exec, s[60:61]
	s_cbranch_vccnz .LBB0_306
	s_add_u32 s6, s6, 0xffffff80
	s_addc_u32 s37, 0, -1
	s_add_u32 s4, s33, s6
	s_addc_u32 s5, s36, s37
	v_lshl_add_u64 v[64:65], s[4:5], 0, v[220:221]
	v_lshlrev_b32_e32 v8, 8, v241
	s_add_u32 s4, s1, s6
	v_and_b32_e32 v60, 0x3800, v8
	v_mov_b32_e32 v61, v221
	s_addc_u32 s5, s3, s37
	v_lshl_add_u64 v[8:9], v[64:65], 0, v[60:61]
	v_lshl_add_u64 v[62:63], s[4:5], 0, v[220:221]
	global_load_dwordx4 v[56:59], v[8:9], off
	v_lshl_add_u64 v[8:9], v[62:63], 0, v[60:61]
	global_load_dwordx4 v[28:31], v[8:9], off
	v_lshlrev_b32_e32 v8, 2, v66
	v_mov_b32_e32 v9, v221
	s_waitcnt lgkmcnt(0)
	v_lshlrev_b32_e32 v66, 16, v47
	v_and_b32_e32 v67, 0xffff0000, v47
	v_lshlrev_b32_e32 v72, 16, v46
	v_and_b32_e32 v73, 0xffff0000, v46
	v_lshlrev_b32_e32 v46, 16, v5
	v_and_b32_e32 v47, 0xffff0000, v5
	v_lshlrev_b32_e32 v74, 16, v4
	v_and_b32_e32 v75, 0xffff0000, v4
	v_lshl_add_u64 v[4:5], s[64:65], 0, v[8:9]
	v_add_co_u32_e32 v12, vcc, s75, v4
	v_lshl_add_u64 v[20:21], v[4:5], 0, s[30:31]
	s_nop 0
	v_addc_co_u32_e32 v13, vcc, 0, v5, vcc
	v_lshlrev_b32_e32 v68, 16, v7
	v_and_b32_e32 v69, 0xffff0000, v7
	v_lshlrev_b32_e32 v70, 16, v6
	v_and_b32_e32 v71, 0xffff0000, v6
	global_load_dwordx4 v[4:7], v[20:21], off offset:16
	global_load_dwordx4 v[8:11], v[20:21], off offset:256
	s_nop 0
	global_load_dwordx4 v[12:15], v[12:13], off
	v_mov_b32_e32 v23, v221
	v_or_b32_e32 v22, 0x4000, v60
	v_lshlrev_b32_e32 v76, 16, v45
	v_and_b32_e32 v77, 0xffff0000, v45
	v_lshlrev_b32_e32 v78, 16, v44
	v_and_b32_e32 v79, 0xffff0000, v44
	v_lshl_add_u64 v[44:45], v[64:65], 0, v[22:23]
	global_load_dwordx4 v[52:55], v[44:45], off
	v_lshl_add_u64 v[22:23], v[62:63], 0, v[22:23]
	global_load_dwordx4 v[48:51], v[22:23], off
	s_nop 0
	global_load_dwordx4 v[20:23], v[20:21], off offset:272
	s_lshl_b64 s[4:5], s[56:57], 12
	s_add_u32 s1, s64, s4
	s_addc_u32 s3, s65, s5
	s_add_u32 s36, s1, s92
	s_addc_u32 s37, s3, 0
	s_waitcnt vmcnt(0)
	v_lshlrev_b32_e32 v44, 16, v59
	v_and_b32_e32 v45, 0xffff0000, v59
	v_lshlrev_b32_e32 v80, 16, v58
	v_and_b32_e32 v81, 0xffff0000, v58
	v_lshlrev_b32_e32 v58, 16, v57
	v_and_b32_e32 v59, 0xffff0000, v57
	v_lshlrev_b32_e32 v82, 16, v56
	v_and_b32_e32 v83, 0xffff0000, v56
	v_pk_fma_f32 v[68:69], v[222:223], v[68:69], v[44:45] neg_lo:[1,0,0] neg_hi:[1,0,0]
	v_pk_fma_f32 v[70:71], v[222:223], v[70:71], v[80:81] neg_lo:[1,0,0] neg_hi:[1,0,0]
	v_pk_fma_f32 v[84:85], v[222:223], v[46:47], v[58:59] neg_lo:[1,0,0] neg_hi:[1,0,0]
	v_lshlrev_b32_e32 v44, 16, v31
	v_and_b32_e32 v45, 0xffff0000, v31
	v_lshlrev_b32_e32 v58, 16, v30
	v_and_b32_e32 v59, 0xffff0000, v30
	v_lshlrev_b32_e32 v30, 16, v29
	v_and_b32_e32 v31, 0xffff0000, v29
	v_lshlrev_b32_e32 v88, 16, v28
	v_and_b32_e32 v89, 0xffff0000, v28
	v_pk_fma_f32 v[80:81], v[222:223], v[74:75], v[82:83] neg_lo:[1,0,0] neg_hi:[1,0,0]
	v_mov_b32_e32 v56, v69
	v_mov_b32_e32 v57, v71
	v_pk_fma_f32 v[74:75], v[222:223], v[66:67], v[44:45] neg_lo:[1,0,0] neg_hi:[1,0,0]
	v_pk_fma_f32 v[90:91], v[222:223], v[76:77], v[30:31] neg_lo:[1,0,0] neg_hi:[1,0,0]
	v_pk_fma_f32 v[76:77], v[222:223], v[78:79], v[88:89] neg_lo:[1,0,0] neg_hi:[1,0,0]
	v_mov_b32_e32 v46, v68
	v_mov_b32_e32 v47, v70
	v_pk_mul_f32 v[28:29], v[56:57], v[56:57]
	v_pk_fma_f32 v[66:67], v[222:223], v[72:73], v[58:59] neg_lo:[1,0,0] neg_hi:[1,0,0]
	v_pk_mul_f32 v[44:45], v[74:75], v[74:75]
	v_pk_mul_f32 v[56:57], v[90:91], v[90:91]
	v_pk_mul_f32 v[58:59], v[76:77], v[76:77]
	v_pk_fma_f32 v[28:29], v[46:47], v[46:47], v[28:29]
	v_pk_mul_f32 v[46:47], v[66:67], v[66:67]
	v_add_f32_e32 v44, v44, v45
	v_add_f32_e32 v45, v56, v57
	v_add_f32_e32 v56, v58, v59
	v_mov_b32_e32 v86, v85
	v_mov_b32_e32 v87, v81
	v_add_f32_e32 v45, v56, v45
	v_add_f32_e32 v46, v46, v47
	v_mov_b32_e32 v82, v84
	v_mov_b32_e32 v83, v80
	v_pk_mul_f32 v[30:31], v[86:87], v[86:87]
	v_add_f32_e32 v45, v46, v45
	v_pk_fma_f32 v[30:31], v[82:83], v[82:83], v[30:31]
	v_add_f32_e32 v44, v44, v45
	v_add_f32_e32 v31, v31, v44
	v_add_f32_e32 v30, v30, v31
	v_add_f32_e32 v29, v29, v30
	v_add_f32_e32 v28, v28, v29
	ds_bpermute_b32 v29, v231, v28
	v_lshlrev_b32_e32 v88, 16, v25
	v_and_b32_e32 v89, 0xffff0000, v25
	s_waitcnt lgkmcnt(0)
	v_lshlrev_b32_e32 v92, 16, v52
	v_and_b32_e32 v93, 0xffff0000, v52
	v_add_f32_e32 v44, v28, v29
	ds_bpermute_b32 v45, v232, v44
	v_or_b32_e32 v28, 0x8000, v60
	v_mov_b32_e32 v29, v221
	v_lshl_add_u64 v[30:31], v[62:63], 0, v[28:29]
	global_load_dwordx4 v[56:59], v[30:31], off
	s_waitcnt lgkmcnt(0)
	v_add_f32_e32 v46, v44, v45
	ds_bpermute_b32 v47, v233, v46
	v_or_b32_e32 v44, 0xc000, v60
	v_mov_b32_e32 v45, v221
	v_lshl_add_u64 v[28:29], v[64:65], 0, v[28:29]
	v_lshlrev_b32_e32 v52, 16, v24
	s_waitcnt lgkmcnt(0)
; __device__ __forceinline__ unsigned cvtpk_s(float lo,float hi){f32x2_t v={lo,hi};bf16x2_t b=__builtin_convertvector(v,bf16x2_t);return __builtin_bit_cast(unsigned,b);}
; template<int THRL> __device__ __forceinline__ void attn_unit(int b,int h,int qb,unsigned char*wsb,char*shm,float kmax,const int CMB,float lam){
;     ...
;     for(int i=0;i<4;++i){const int row=i*8+(lane>>3); float a_[16]; float ss=0.f;
;       #pragma unroll
;       for(int t=0;t<2;++t)
;         #pragma unroll
;         for(int e=0;e<4;++e){const unsigned w1=p1[t][i][e],w2=mine[t][i][e];
;           const float x0=__uint_as_float(w1<<16)-lam*__uint_as_float(w2<<16), x1=__uint_as_float(w1&0xffff0000u)-lam*__uint_as_float(w2&0xffff0000u);
;           a_[t*8+2*e]=x0;a_[t*8+2*e+1]=x1;ss+=x0*x0+x1*x1;}
;       ss+=__shfl_xor(ss,1);ss+=__shfl_xor(ss,2);ss+=__shfl_xor(ss,4);
;       const float rn=1.0f/sqrtf(ss*(1.f/128.f)+1e-6f);
;       u32x4 ylo,yhi;
;       #pragma unroll
;       for(int e=0;e<4;++e){ylo[e]=cvtpk_s(a_[2*e]*rn*swl[2*e],a_[2*e+1]*rn*swl[2*e+1]);yhi[e]=cvtpk_s(a_[8+2*e]*rn*swh[2*e],a_[8+2*e+1]*rn*swh[2*e+1]);}
;       *(u32x4*)(Yw+(long)row*ya_pitch)=ylo; *(u32x4*)(Yw+(long)row*ya_pitch+64)=yhi; }
	v_add_f32_e32 v30, v46, v47
	v_fmamk_f32 v30, v30, 0x3c000000, v239
	v_mul_f32_e32 v31, 0x4f800000, v30
	v_cmp_gt_f32_e32 vcc, s74, v30
	s_nop 1
	v_cndmask_b32_e32 v46, v30, v31, vcc
	v_sqrt_f32_e32 v47, v46
	v_lshl_add_u64 v[30:31], v[62:63], 0, v[44:45]
	v_lshl_add_u64 v[44:45], v[64:65], 0, v[44:45]
	global_load_dwordx4 v[60:63], v[28:29], off
	s_nop 0
	global_load_dwordx4 v[28:31], v[30:31], off
	v_add_u32_e32 v72, -1, v47
	v_fma_f32 v73, -v72, v47, v46
	v_cmp_ge_f32_e64 s[4:5], 0, v73
	v_add_u32_e32 v73, 1, v47
	s_nop 0
	v_cndmask_b32_e64 v72, v47, v72, s[4:5]
	v_fma_f32 v47, -v73, v47, v46
	v_cmp_lt_f32_e64 s[4:5], 0, v47
	s_nop 1
	v_cndmask_b32_e64 v47, v72, v73, s[4:5]
	v_mul_f32_e32 v72, 0x37800000, v47
	v_cndmask_b32_e32 v47, v47, v72, vcc
	v_cmp_class_f32_e32 vcc, v46, v237
	v_lshl_add_u64 v[72:73], s[36:37], 0, v[220:221]
	s_nop 0
	v_cndmask_b32_e32 v78, v47, v46, vcc
	v_div_scale_f32 v79, s[4:5], v78, v78, 1.0
	v_rcp_f32_e32 v82, v79
	global_load_dwordx4 v[44:47], v[44:45], off
	v_fma_f32 v64, -v79, v82, 1.0
	v_fmac_f32_e32 v82, v64, v82
	v_div_scale_f32 v64, vcc, 1.0, v78, 1.0
	v_mul_f32_e32 v65, v64, v82
	v_fma_f32 v83, -v79, v65, v64
	v_fmac_f32_e32 v65, v83, v82
	v_fma_f32 v64, -v79, v65, v64
	v_div_fmas_f32 v64, v64, v82, v65
	v_div_fixup_f32 v86, v64, v78, 1.0
	v_pk_mul_f32 v[64:65], v[76:77], v[86:87] op_sel_hi:[1,0]
	v_pk_mul_f32 v[78:79], v[66:67], v[86:87] op_sel_hi:[1,0]
	v_pk_mul_f32 v[64:65], v[12:13], v[64:65]
	v_lshlrev_b32_e32 v66, 16, v27
	v_cvt_pk_bf16_f32 v76, v64, v65
	v_pk_mul_f32 v[64:65], v[80:81], v[86:87] op_sel_hi:[1,0]
	v_and_b32_e32 v67, 0xffff0000, v27
	v_pk_mul_f32 v[64:65], v[8:9], v[64:65]
	v_lshlrev_b32_e32 v82, 16, v43
	v_cvt_pk_bf16_f32 v80, v64, v65
	v_pk_mul_f32 v[64:65], v[90:91], v[86:87] op_sel_hi:[1,0]
	v_and_b32_e32 v83, 0xffff0000, v43
	v_pk_mul_f32 v[64:65], v[14:15], v[64:65]
	v_lshlrev_b32_e32 v90, 16, v41
	v_cvt_pk_bf16_f32 v77, v64, v65
	v_pk_mul_f32 v[64:65], v[84:85], v[86:87] op_sel_hi:[1,0]
	v_lshlrev_b32_e32 v84, 16, v54
	v_pk_mul_f32 v[64:65], v[10:11], v[64:65]
	v_and_b32_e32 v85, 0xffff0000, v54
	v_cvt_pk_bf16_f32 v81, v64, v65
	v_lshlrev_b32_e32 v64, 16, v55
	v_and_b32_e32 v65, 0xffff0000, v55
	v_lshlrev_b32_e32 v54, 16, v26
	v_and_b32_e32 v55, 0xffff0000, v26
	v_pk_fma_f32 v[64:65], v[222:223], v[66:67], v[64:65] neg_lo:[1,0,0] neg_hi:[1,0,0]
	v_pk_fma_f32 v[54:55], v[222:223], v[54:55], v[84:85] neg_lo:[1,0,0] neg_hi:[1,0,0]
	v_mov_b32_e32 v84, v65
	v_mov_b32_e32 v85, v55
	v_mov_b32_e32 v26, v64
	v_mov_b32_e32 v27, v54
	v_pk_mul_f32 v[84:85], v[84:85], v[84:85]
	v_lshlrev_b32_e32 v66, 16, v51
	v_and_b32_e32 v67, 0xffff0000, v51
	v_pk_fma_f32 v[26:27], v[26:27], v[26:27], v[84:85]
	v_lshlrev_b32_e32 v84, 16, v50
	v_and_b32_e32 v85, 0xffff0000, v50
	v_lshlrev_b32_e32 v50, 16, v42
	v_and_b32_e32 v51, 0xffff0000, v42
	v_pk_fma_f32 v[42:43], v[222:223], v[50:51], v[84:85] neg_lo:[1,0,0] neg_hi:[1,0,0]
	v_lshlrev_b32_e32 v50, 16, v53
	v_and_b32_e32 v51, 0xffff0000, v53
	v_and_b32_e32 v53, 0xffff0000, v24
	v_pk_fma_f32 v[50:51], v[222:223], v[88:89], v[50:51] neg_lo:[1,0,0] neg_hi:[1,0,0]
	v_pk_fma_f32 v[52:53], v[222:223], v[52:53], v[92:93] neg_lo:[1,0,0] neg_hi:[1,0,0]
	v_mov_b32_e32 v92, v51
	v_mov_b32_e32 v93, v53
	v_mov_b32_e32 v24, v50
	v_mov_b32_e32 v25, v52
	v_pk_mul_f32 v[92:93], v[92:93], v[92:93]
	v_lshlrev_b32_e32 v88, 16, v49
	v_and_b32_e32 v89, 0xffff0000, v49
	v_and_b32_e32 v91, 0xffff0000, v41
	v_pk_fma_f32 v[24:25], v[24:25], v[24:25], v[92:93]
	v_lshlrev_b32_e32 v92, 16, v48
	v_and_b32_e32 v93, 0xffff0000, v48
	v_lshlrev_b32_e32 v48, 16, v40
	v_and_b32_e32 v49, 0xffff0000, v40
	v_pk_fma_f32 v[66:67], v[222:223], v[82:83], v[66:67] neg_lo:[1,0,0] neg_hi:[1,0,0]
	v_pk_fma_f32 v[88:89], v[222:223], v[90:91], v[88:89] neg_lo:[1,0,0] neg_hi:[1,0,0]
	v_pk_fma_f32 v[40:41], v[222:223], v[48:49], v[92:93] neg_lo:[1,0,0] neg_hi:[1,0,0]
	v_pk_mul_f32 v[82:83], v[66:67], v[66:67]
	v_pk_mul_f32 v[90:91], v[88:89], v[88:89]
	v_pk_mul_f32 v[48:49], v[40:41], v[40:41]
	v_pk_mul_f32 v[84:85], v[42:43], v[42:43]
	v_add_f32_e32 v82, v82, v83
	v_add_f32_e32 v83, v90, v91
	v_add_f32_e32 v48, v48, v49
	v_add_f32_e32 v48, v48, v83
	v_add_f32_e32 v49, v84, v85
	v_add_f32_e32 v48, v49, v48
	v_add_f32_e32 v48, v82, v48
	v_add_f32_e32 v25, v25, v48
	v_add_f32_e32 v24, v24, v25
	v_add_f32_e32 v24, v27, v24
	v_add_f32_e32 v26, v26, v24
	ds_bpermute_b32 v27, v231, v26
	v_pk_mul_f32 v[24:25], v[4:5], v[78:79]
	s_waitcnt lgkmcnt(0)
	v_add_f32_e32 v26, v26, v27
	ds_bpermute_b32 v27, v232, v26
	v_cvt_pk_bf16_f32 v78, v24, v25
	v_pk_mul_f32 v[24:25], v[70:71], v[86:87] op_sel_hi:[1,0]
	s_waitcnt lgkmcnt(0)
	v_add_f32_e32 v26, v26, v27
	v_pk_mul_f32 v[24:25], v[20:21], v[24:25]
	ds_bpermute_b32 v27, v233, v26
	v_cvt_pk_bf16_f32 v82, v24, v25
	v_pk_mul_f32 v[24:25], v[74:75], v[86:87] op_sel_hi:[1,0]
	v_lshlrev_b32_e32 v74, 16, v17
	v_pk_mul_f32 v[24:25], v[6:7], v[24:25]
	v_and_b32_e32 v75, 0xffff0000, v17
	v_cvt_pk_bf16_f32 v79, v24, v25
	v_pk_mul_f32 v[24:25], v[68:69], v[86:87] op_sel_hi:[1,0]
	s_nop 0
	v_pk_mul_f32 v[24:25], v[22:23], v[24:25]
	s_nop 0
	v_cvt_pk_bf16_f32 v83, v24, v25
	s_waitcnt lgkmcnt(0)
; __device__ __forceinline__ unsigned cvtpk_s(float lo,float hi){f32x2_t v={lo,hi};bf16x2_t b=__builtin_convertvector(v,bf16x2_t);return __builtin_bit_cast(unsigned,b);}
; template<int THRL> __device__ __forceinline__ void attn_unit(int b,int h,int qb,unsigned char*wsb,char*shm,float kmax,const int CMB,float lam){
;     ...
;     for(int i=0;i<4;++i){const int row=i*8+(lane>>3); float a_[16]; float ss=0.f;
;       #pragma unroll
;       for(int t=0;t<2;++t)
;         #pragma unroll
;         for(int e=0;e<4;++e){const unsigned w1=p1[t][i][e],w2=mine[t][i][e];
;           const float x0=__uint_as_float(w1<<16)-lam*__uint_as_float(w2<<16), x1=__uint_as_float(w1&0xffff0000u)-lam*__uint_as_float(w2&0xffff0000u);
;           a_[t*8+2*e]=x0;a_[t*8+2*e+1]=x1;ss+=x0*x0+x1*x1;}
;       ss+=__shfl_xor(ss,1);ss+=__shfl_xor(ss,2);ss+=__shfl_xor(ss,4);
;       const float rn=1.0f/sqrtf(ss*(1.f/128.f)+1e-6f);
;       u32x4 ylo,yhi;
;       #pragma unroll
;       for(int e=0;e<4;++e){ylo[e]=cvtpk_s(a_[2*e]*rn*swl[2*e],a_[2*e+1]*rn*swl[2*e+1]);yhi[e]=cvtpk_s(a_[8+2*e]*rn*swh[2*e],a_[8+2*e+1]*rn*swh[2*e+1]);}
;       *(u32x4*)(Yw+(long)row*ya_pitch)=ylo; *(u32x4*)(Yw+(long)row*ya_pitch+64)=yhi; }
	v_add_f32_e32 v25, v26, v27
	v_fmamk_f32 v25, v25, 0x3c000000, v239
	v_mul_f32_e32 v26, 0x4f800000, v25
	v_cmp_gt_f32_e32 vcc, s74, v25
	v_lshlrev_b32_e32 v24, 9, v241
	v_and_b32_e32 v220, 0x7000, v24
	v_cndmask_b32_e32 v48, v25, v26, vcc
	v_sqrt_f32_e32 v49, v48
	v_lshl_add_u64 v[24:25], v[72:73], 0, v[220:221]
	v_lshl_add_u64 v[26:27], v[24:25], 0, s[34:35]
	v_add_u32_e32 v68, -1, v49
	v_fma_f32 v69, -v68, v49, v48
	v_cmp_ge_f32_e64 s[4:5], 0, v69
	v_add_u32_e32 v69, 1, v49
	s_nop 0
	v_cndmask_b32_e64 v68, v49, v68, s[4:5]
	v_fma_f32 v49, -v69, v49, v48
	v_cmp_lt_f32_e64 s[4:5], 0, v49
	s_nop 1
	v_cndmask_b32_e64 v49, v68, v69, s[4:5]
	v_mul_f32_e32 v68, 0x37800000, v49
	v_cndmask_b32_e32 v49, v49, v68, vcc
	v_cmp_class_f32_e32 vcc, v48, v237
	s_nop 1
	v_cndmask_b32_e32 v68, v49, v48, vcc
	v_div_scale_f32 v69, s[4:5], v68, v68, 1.0
	v_rcp_f32_e32 v70, v69
	v_add_co_u32_e32 v48, vcc, s76, v24
	s_nop 1
	v_addc_co_u32_e32 v49, vcc, 0, v25, vcc
	global_store_dwordx4 v[48:49], v[76:79], off
	global_store_dwordx4 v[26:27], v[80:83], off offset:128
	v_fma_f32 v26, -v69, v70, 1.0
	v_fmac_f32_e32 v70, v26, v70
	v_div_scale_f32 v26, vcc, 1.0, v68, 1.0
	v_mul_f32_e32 v27, v26, v70
	v_fma_f32 v48, -v69, v27, v26
	v_fmac_f32_e32 v27, v48, v70
	v_fma_f32 v26, -v69, v27, v26
	v_div_fmas_f32 v26, v26, v70, v27
	v_div_fixup_f32 v72, v26, v68, 1.0
	v_pk_mul_f32 v[26:27], v[40:41], v[72:73] op_sel_hi:[1,0]
	v_lshlrev_b32_e32 v40, 16, v19
	v_pk_mul_f32 v[26:27], v[12:13], v[26:27]
	v_and_b32_e32 v41, 0xffff0000, v19
	v_cvt_pk_bf16_f32 v68, v26, v27
	v_pk_mul_f32 v[26:27], v[52:53], v[72:73] op_sel_hi:[1,0]
	v_lshlrev_b32_e32 v48, 16, v39
	v_pk_mul_f32 v[26:27], v[8:9], v[26:27]
	v_and_b32_e32 v49, 0xffff0000, v39
	v_cvt_pk_bf16_f32 v52, v26, v27
	v_pk_mul_f32 v[26:27], v[88:89], v[72:73] op_sel_hi:[1,0]
	s_waitcnt vmcnt(0)
	v_lshlrev_b32_e32 v78, 16, v60
	v_pk_mul_f32 v[26:27], v[14:15], v[26:27]
	v_and_b32_e32 v79, 0xffff0000, v60
	v_cvt_pk_bf16_f32 v69, v26, v27
	v_lshlrev_b32_e32 v26, 16, v63
	v_and_b32_e32 v27, 0xffff0000, v63
	v_pk_fma_f32 v[26:27], v[222:223], v[40:41], v[26:27] neg_lo:[1,0,0] neg_hi:[1,0,0]
	v_lshlrev_b32_e32 v40, 16, v59
	v_and_b32_e32 v41, 0xffff0000, v59
	v_pk_fma_f32 v[40:41], v[222:223], v[48:49], v[40:41] neg_lo:[1,0,0] neg_hi:[1,0,0]
	v_lshlrev_b32_e32 v48, 16, v62
	v_and_b32_e32 v49, 0xffff0000, v62
	v_lshlrev_b32_e32 v62, 16, v18
	v_and_b32_e32 v63, 0xffff0000, v18
	v_pk_fma_f32 v[18:19], v[222:223], v[62:63], v[48:49] neg_lo:[1,0,0] neg_hi:[1,0,0]
	v_mov_b32_e32 v62, v27
	v_mov_b32_e32 v63, v19
	v_mov_b32_e32 v48, v26
	v_mov_b32_e32 v49, v18
	v_pk_mul_f32 v[62:63], v[62:63], v[62:63]
	v_and_b32_e32 v59, 0xffff0000, v38
	v_pk_fma_f32 v[62:63], v[48:49], v[48:49], v[62:63]
	v_lshlrev_b32_e32 v48, 16, v58
	v_and_b32_e32 v49, 0xffff0000, v58
	v_lshlrev_b32_e32 v58, 16, v38
	v_pk_fma_f32 v[38:39], v[222:223], v[58:59], v[48:49] neg_lo:[1,0,0] neg_hi:[1,0,0]
	v_lshlrev_b32_e32 v48, 16, v61
	v_and_b32_e32 v49, 0xffff0000, v61
	v_lshlrev_b32_e32 v60, 16, v16
	v_and_b32_e32 v61, 0xffff0000, v16
	v_pk_fma_f32 v[48:49], v[222:223], v[74:75], v[48:49] neg_lo:[1,0,0] neg_hi:[1,0,0]
	v_pk_fma_f32 v[16:17], v[222:223], v[60:61], v[78:79] neg_lo:[1,0,0] neg_hi:[1,0,0]
	v_mov_b32_e32 v78, v49
	v_mov_b32_e32 v79, v17
	v_mov_b32_e32 v60, v48
	v_mov_b32_e32 v61, v16
	v_pk_mul_f32 v[78:79], v[78:79], v[78:79]
	v_lshlrev_b32_e32 v74, 16, v57
	v_and_b32_e32 v75, 0xffff0000, v57
	v_lshlrev_b32_e32 v76, 16, v37
	v_and_b32_e32 v77, 0xffff0000, v37
	v_pk_fma_f32 v[60:61], v[60:61], v[60:61], v[78:79]
	v_lshlrev_b32_e32 v78, 16, v56
	v_and_b32_e32 v79, 0xffff0000, v56
	v_lshlrev_b32_e32 v56, 16, v36
	v_and_b32_e32 v57, 0xffff0000, v36
	v_pk_fma_f32 v[74:75], v[222:223], v[76:77], v[74:75] neg_lo:[1,0,0] neg_hi:[1,0,0]
	v_pk_fma_f32 v[36:37], v[222:223], v[56:57], v[78:79] neg_lo:[1,0,0] neg_hi:[1,0,0]
	v_pk_mul_f32 v[70:71], v[40:41], v[40:41]
	v_pk_mul_f32 v[76:77], v[74:75], v[74:75]
	v_pk_mul_f32 v[56:57], v[36:37], v[36:37]
	v_pk_mul_f32 v[58:59], v[38:39], v[38:39]
	v_add_f32_e32 v53, v70, v71
	v_add_f32_e32 v70, v76, v77
	v_add_f32_e32 v56, v56, v57
	v_add_f32_e32 v56, v56, v70
	v_add_f32_e32 v57, v58, v59
	v_add_f32_e32 v56, v57, v56
	v_add_f32_e32 v53, v53, v56
	v_add_f32_e32 v53, v61, v53
	v_add_f32_e32 v53, v60, v53
	v_add_f32_e32 v53, v63, v53
	v_add_f32_e32 v56, v62, v53
	ds_bpermute_b32 v57, v231, v56
	v_pk_mul_f32 v[50:51], v[50:51], v[72:73] op_sel_hi:[1,0]
	v_pk_mul_f32 v[42:43], v[42:43], v[72:73] op_sel_hi:[1,0]
	v_pk_mul_f32 v[50:51], v[10:11], v[50:51]
	v_pk_mul_f32 v[42:43], v[4:5], v[42:43]
	v_cvt_pk_bf16_f32 v53, v50, v51
	s_waitcnt lgkmcnt(0)
	v_add_f32_e32 v50, v56, v57
	ds_bpermute_b32 v51, v232, v50
	v_cvt_pk_bf16_f32 v70, v42, v43
	v_pk_mul_f32 v[42:43], v[54:55], v[72:73] op_sel_hi:[1,0]
	v_and_b32_e32 v57, 0xffff0000, v46
	v_pk_mul_f32 v[42:43], v[20:21], v[42:43]
	s_waitcnt lgkmcnt(0)
	v_add_f32_e32 v50, v50, v51
	ds_bpermute_b32 v51, v233, v50
	v_cvt_pk_bf16_f32 v54, v42, v43
	v_pk_mul_f32 v[42:43], v[66:67], v[72:73] op_sel_hi:[1,0]
	v_lshlrev_b32_e32 v58, 16, v1
	v_pk_mul_f32 v[42:43], v[6:7], v[42:43]
	v_and_b32_e32 v59, 0xffff0000, v1
	v_cvt_pk_bf16_f32 v71, v42, v43
	s_waitcnt lgkmcnt(0)
; __device__ __forceinline__ unsigned cvtpk_s(float lo,float hi){f32x2_t v={lo,hi};bf16x2_t b=__builtin_convertvector(v,bf16x2_t);return __builtin_bit_cast(unsigned,b);}
; template<int THRL> __device__ __forceinline__ void attn_unit(int b,int h,int qb,unsigned char*wsb,char*shm,float kmax,const int CMB,float lam){
;     ...
;     for(int i=0;i<4;++i){const int row=i*8+(lane>>3); float a_[16]; float ss=0.f;
;       #pragma unroll
;       for(int t=0;t<2;++t)
;         #pragma unroll
;         for(int e=0;e<4;++e){const unsigned w1=p1[t][i][e],w2=mine[t][i][e];
;           const float x0=__uint_as_float(w1<<16)-lam*__uint_as_float(w2<<16), x1=__uint_as_float(w1&0xffff0000u)-lam*__uint_as_float(w2&0xffff0000u);
;           a_[t*8+2*e]=x0;a_[t*8+2*e+1]=x1;ss+=x0*x0+x1*x1;}
;       ss+=__shfl_xor(ss,1);ss+=__shfl_xor(ss,2);ss+=__shfl_xor(ss,4);
;       const float rn=1.0f/sqrtf(ss*(1.f/128.f)+1e-6f);
;       u32x4 ylo,yhi;
;       #pragma unroll
;       for(int e=0;e<4;++e){ylo[e]=cvtpk_s(a_[2*e]*rn*swl[2*e],a_[2*e+1]*rn*swl[2*e+1]);yhi[e]=cvtpk_s(a_[8+2*e]*rn*swh[2*e],a_[8+2*e+1]*rn*swh[2*e+1]);}
;       *(u32x4*)(Yw+(long)row*ya_pitch)=ylo; *(u32x4*)(Yw+(long)row*ya_pitch+64)=yhi; }
	v_add_f32_e32 v42, v50, v51
	v_fmamk_f32 v42, v42, 0x3c000000, v239
	v_mul_f32_e32 v43, 0x4f800000, v42
	v_cmp_gt_f32_e32 vcc, s74, v42
	v_lshlrev_b32_e32 v62, 16, v44
	v_and_b32_e32 v63, 0xffff0000, v44
	v_cndmask_b32_e32 v50, v42, v43, vcc
	v_sqrt_f32_e32 v51, v50
	v_pk_mul_f32 v[42:43], v[64:65], v[72:73] op_sel_hi:[1,0]
	v_lshlrev_b32_e32 v44, 16, v0
	v_pk_mul_f32 v[42:43], v[22:23], v[42:43]
	v_lshlrev_b32_e32 v60, 16, v33
	v_cvt_pk_bf16_f32 v55, v42, v43
	v_add_u32_e32 v42, -1, v51
	v_fma_f32 v43, -v42, v51, v50
	v_cmp_ge_f32_e64 s[4:5], 0, v43
	v_add_u32_e32 v43, 1, v51
	v_and_b32_e32 v61, 0xffff0000, v33
	v_cndmask_b32_e64 v42, v51, v42, s[4:5]
	v_fma_f32 v51, -v43, v51, v50
	v_cmp_lt_f32_e64 s[4:5], 0, v51
	s_nop 1
	v_cndmask_b32_e64 v42, v42, v43, s[4:5]
	v_mul_f32_e32 v43, 0x37800000, v42
	v_cndmask_b32_e32 v42, v42, v43, vcc
	v_cmp_class_f32_e32 vcc, v50, v237
	s_nop 1
	v_cndmask_b32_e32 v50, v42, v50, vcc
	v_div_scale_f32 v51, s[4:5], v50, v50, 1.0
	v_rcp_f32_e32 v56, v51
	v_add_co_u32_e32 v42, vcc, s77, v24
	s_nop 1
	v_addc_co_u32_e32 v43, vcc, 0, v25, vcc
	global_store_dwordx4 v[42:43], v[68:71], off
	global_store_dwordx4 v[42:43], v[52:55], off offset:128
	v_fma_f32 v42, -v51, v56, 1.0
	v_fmac_f32_e32 v56, v42, v56
	v_div_scale_f32 v42, vcc, 1.0, v50, 1.0
	v_mul_f32_e32 v43, v42, v56
	v_fma_f32 v52, -v51, v43, v42
	v_fmac_f32_e32 v43, v52, v56
	v_fma_f32 v42, -v51, v43, v42
	v_div_fmas_f32 v42, v42, v56, v43
	v_div_fixup_f32 v42, v42, v50, 1.0
	v_pk_mul_f32 v[36:37], v[36:37], v[42:43] op_sel_hi:[1,0]
	v_pk_mul_f32 v[50:51], v[74:75], v[42:43] op_sel_hi:[1,0]
	v_pk_mul_f32 v[36:37], v[12:13], v[36:37]
	v_pk_mul_f32 v[50:51], v[14:15], v[50:51]
	v_cvt_pk_bf16_f32 v36, v36, v37
	v_cvt_pk_bf16_f32 v37, v50, v51
	v_lshlrev_b32_e32 v50, 16, v47
	v_and_b32_e32 v51, 0xffff0000, v47
	v_lshlrev_b32_e32 v52, 16, v3
	v_and_b32_e32 v53, 0xffff0000, v3
	v_lshlrev_b32_e32 v56, 16, v46
	v_lshlrev_b32_e32 v46, 16, v2
	v_and_b32_e32 v47, 0xffff0000, v2
	v_pk_fma_f32 v[50:51], v[222:223], v[52:53], v[50:51] neg_lo:[1,0,0] neg_hi:[1,0,0]
	v_pk_fma_f32 v[46:47], v[222:223], v[46:47], v[56:57] neg_lo:[1,0,0] neg_hi:[1,0,0]
	v_mov_b32_e32 v56, v51
	v_mov_b32_e32 v57, v47
	v_mov_b32_e32 v2, v50
	v_mov_b32_e32 v3, v46
	v_pk_mul_f32 v[56:57], v[56:57], v[56:57]
	v_lshlrev_b32_e32 v52, 16, v31
	v_and_b32_e32 v53, 0xffff0000, v31
	v_pk_fma_f32 v[2:3], v[2:3], v[2:3], v[56:57]
	v_lshlrev_b32_e32 v56, 16, v30
	v_and_b32_e32 v57, 0xffff0000, v30
	v_lshlrev_b32_e32 v30, 16, v34
	v_and_b32_e32 v31, 0xffff0000, v34
	v_pk_fma_f32 v[30:31], v[222:223], v[30:31], v[56:57] neg_lo:[1,0,0] neg_hi:[1,0,0]
	v_lshlrev_b32_e32 v56, 16, v45
	v_and_b32_e32 v57, 0xffff0000, v45
	v_and_b32_e32 v45, 0xffff0000, v0
	v_pk_fma_f32 v[56:57], v[222:223], v[58:59], v[56:57] neg_lo:[1,0,0] neg_hi:[1,0,0]
	v_pk_fma_f32 v[44:45], v[222:223], v[44:45], v[62:63] neg_lo:[1,0,0] neg_hi:[1,0,0]
	v_mov_b32_e32 v62, v57
	v_mov_b32_e32 v63, v45
	v_mov_b32_e32 v0, v56
	v_mov_b32_e32 v1, v44
	v_pk_mul_f32 v[62:63], v[62:63], v[62:63]
	v_lshlrev_b32_e32 v58, 16, v29
	v_and_b32_e32 v59, 0xffff0000, v29
	v_pk_fma_f32 v[0:1], v[0:1], v[0:1], v[62:63]
	v_lshlrev_b32_e32 v62, 16, v28
	v_and_b32_e32 v63, 0xffff0000, v28
	v_lshlrev_b32_e32 v28, 16, v32
	v_and_b32_e32 v29, 0xffff0000, v32
	v_pk_fma_f32 v[58:59], v[222:223], v[60:61], v[58:59] neg_lo:[1,0,0] neg_hi:[1,0,0]
	v_pk_fma_f32 v[28:29], v[222:223], v[28:29], v[62:63] neg_lo:[1,0,0] neg_hi:[1,0,0]
	v_lshlrev_b32_e32 v54, 16, v35
	v_and_b32_e32 v55, 0xffff0000, v35
	v_pk_mul_f32 v[60:61], v[58:59], v[58:59]
	v_pk_mul_f32 v[32:33], v[28:29], v[28:29]
	v_pk_mul_f32 v[16:17], v[16:17], v[42:43] op_sel_hi:[1,0]
	v_pk_fma_f32 v[52:53], v[222:223], v[54:55], v[52:53] neg_lo:[1,0,0] neg_hi:[1,0,0]
	v_pk_mul_f32 v[34:35], v[30:31], v[30:31]
	v_add_f32_e32 v43, v60, v61
	v_add_f32_e32 v32, v32, v33
	v_pk_mul_f32 v[16:17], v[8:9], v[16:17]
	v_pk_mul_f32 v[54:55], v[52:53], v[52:53]
	v_add_f32_e32 v32, v32, v43
	v_add_f32_e32 v33, v34, v35
	v_cvt_pk_bf16_f32 v16, v16, v17
	v_add_f32_e32 v17, v54, v55
	v_add_f32_e32 v32, v33, v32
	v_add_f32_e32 v17, v17, v32
	v_add_f32_e32 v1, v1, v17
	v_add_f32_e32 v0, v0, v1
	v_add_f32_e32 v0, v3, v0
	v_add_f32_e32 v2, v2, v0
	ds_bpermute_b32 v3, v231, v2
	v_pk_mul_f32 v[0:1], v[48:49], v[42:43] op_sel_hi:[1,0]
	s_waitcnt lgkmcnt(0)
; __device__ __forceinline__ unsigned cvtpk_s(float lo,float hi){f32x2_t v={lo,hi};bf16x2_t b=__builtin_convertvector(v,bf16x2_t);return __builtin_bit_cast(unsigned,b);}
; template<int THRL> __device__ __forceinline__ void attn_unit(int b,int h,int qb,unsigned char*wsb,char*shm,float kmax,const int CMB,float lam){
;     ...
;     for(int i=0;i<4;++i){const int row=i*8+(lane>>3); float a_[16]; float ss=0.f;
;       #pragma unroll
;       for(int t=0;t<2;++t)
;         #pragma unroll
;         for(int e=0;e<4;++e){const unsigned w1=p1[t][i][e],w2=mine[t][i][e];
;           const float x0=__uint_as_float(w1<<16)-lam*__uint_as_float(w2<<16), x1=__uint_as_float(w1&0xffff0000u)-lam*__uint_as_float(w2&0xffff0000u);
;           a_[t*8+2*e]=x0;a_[t*8+2*e+1]=x1;ss+=x0*x0+x1*x1;}
;       ss+=__shfl_xor(ss,1);ss+=__shfl_xor(ss,2);ss+=__shfl_xor(ss,4);
;       const float rn=1.0f/sqrtf(ss*(1.f/128.f)+1e-6f);
;       u32x4 ylo,yhi;
;       #pragma unroll
;       for(int e=0;e<4;++e){ylo[e]=cvtpk_s(a_[2*e]*rn*swl[2*e],a_[2*e+1]*rn*swl[2*e+1]);yhi[e]=cvtpk_s(a_[8+2*e]*rn*swh[2*e],a_[8+2*e+1]*rn*swh[2*e+1]);}
;       *(u32x4*)(Yw+(long)row*ya_pitch)=ylo; *(u32x4*)(Yw+(long)row*ya_pitch+64)=yhi; }
	v_add_f32_e32 v2, v2, v3
	ds_bpermute_b32 v3, v232, v2
	v_pk_mul_f32 v[0:1], v[10:11], v[0:1]
	s_waitcnt lgkmcnt(0)
	v_add_f32_e32 v2, v2, v3
	v_cvt_pk_bf16_f32 v17, v0, v1
	v_pk_mul_f32 v[0:1], v[38:39], v[42:43] op_sel_hi:[1,0]
	ds_bpermute_b32 v3, v233, v2
	v_pk_mul_f32 v[0:1], v[4:5], v[0:1]
	s_nop 0
	v_cvt_pk_bf16_f32 v38, v0, v1
	v_pk_mul_f32 v[0:1], v[18:19], v[42:43] op_sel_hi:[1,0]
	s_nop 0
	v_pk_mul_f32 v[0:1], v[20:21], v[0:1]
	s_nop 0
	v_cvt_pk_bf16_f32 v18, v0, v1
	v_pk_mul_f32 v[0:1], v[40:41], v[42:43] op_sel_hi:[1,0]
	s_nop 0
	v_pk_mul_f32 v[0:1], v[6:7], v[0:1]
	s_nop 0
	v_cvt_pk_bf16_f32 v39, v0, v1
	s_waitcnt lgkmcnt(0)
	v_add_f32_e32 v0, v2, v3
	v_fmamk_f32 v0, v0, 0x3c000000, v239
	v_mul_f32_e32 v1, 0x4f800000, v0
	v_cmp_gt_f32_e32 vcc, s74, v0
	s_nop 1
	v_cndmask_b32_e32 v2, v0, v1, vcc
	v_sqrt_f32_e32 v3, v2
	v_pk_mul_f32 v[0:1], v[26:27], v[42:43] op_sel_hi:[1,0]
	s_nop 0
	v_pk_mul_f32 v[0:1], v[22:23], v[0:1]
	s_nop 0
	v_cvt_pk_bf16_f32 v19, v0, v1
	v_add_u32_e32 v0, -1, v3
	v_fma_f32 v1, -v0, v3, v2
	v_cmp_ge_f32_e64 s[4:5], 0, v1
	v_add_u32_e32 v1, 1, v3
	s_nop 0
	v_cndmask_b32_e64 v0, v3, v0, s[4:5]
	v_fma_f32 v3, -v1, v3, v2
	v_cmp_lt_f32_e64 s[4:5], 0, v3
	s_nop 1
	v_cndmask_b32_e64 v0, v0, v1, s[4:5]
	v_mul_f32_e32 v1, 0x37800000, v0
	v_cndmask_b32_e32 v0, v0, v1, vcc
	v_cmp_class_f32_e32 vcc, v2, v237
	s_nop 1
	v_cndmask_b32_e32 v2, v0, v2, vcc
	v_div_scale_f32 v3, s[4:5], v2, v2, 1.0
	v_rcp_f32_e32 v26, v3
	v_add_co_u32_e32 v0, vcc, s78, v24
	s_nop 1
	v_addc_co_u32_e32 v1, vcc, 0, v25, vcc
	global_store_dwordx4 v[0:1], v[36:39], off
	global_store_dwordx4 v[0:1], v[16:19], off offset:128
	v_fma_f32 v0, -v3, v26, 1.0
	v_fmac_f32_e32 v26, v0, v26
	v_div_scale_f32 v0, vcc, 1.0, v2, 1.0
	v_mul_f32_e32 v1, v0, v26
	v_fma_f32 v16, -v3, v1, v0
	v_fmac_f32_e32 v1, v16, v26
	v_fma_f32 v0, -v3, v1, v0
	v_div_fmas_f32 v0, v0, v26, v1
	v_div_fixup_f32 v16, v0, v2, 1.0
	v_pk_mul_f32 v[2:3], v[44:45], v[16:17] op_sel_hi:[1,0]
	v_pk_mul_f32 v[0:1], v[28:29], v[16:17] op_sel_hi:[1,0]
	v_pk_mul_f32 v[2:3], v[8:9], v[2:3]
	v_pk_mul_f32 v[0:1], v[12:13], v[0:1]
	v_cvt_pk_bf16_f32 v8, v2, v3
	v_pk_mul_f32 v[2:3], v[58:59], v[16:17] op_sel_hi:[1,0]
	v_cvt_pk_bf16_f32 v0, v0, v1
	v_pk_mul_f32 v[2:3], v[14:15], v[2:3]
	s_nop 0
	v_cvt_pk_bf16_f32 v1, v2, v3
	v_pk_mul_f32 v[2:3], v[56:57], v[16:17] op_sel_hi:[1,0]
	s_nop 0
	v_pk_mul_f32 v[2:3], v[10:11], v[2:3]
	s_nop 0
	v_cvt_pk_bf16_f32 v9, v2, v3
	v_pk_mul_f32 v[2:3], v[30:31], v[16:17] op_sel_hi:[1,0]
	s_nop 0
	v_pk_mul_f32 v[2:3], v[4:5], v[2:3]
	v_pk_mul_f32 v[4:5], v[46:47], v[16:17] op_sel_hi:[1,0]
	v_cvt_pk_bf16_f32 v2, v2, v3
	v_pk_mul_f32 v[4:5], v[20:21], v[4:5]
	s_nop 0
	v_cvt_pk_bf16_f32 v10, v4, v5
	v_pk_mul_f32 v[4:5], v[52:53], v[16:17] op_sel_hi:[1,0]
	s_nop 0
	v_pk_mul_f32 v[4:5], v[6:7], v[4:5]
	s_nop 0
	v_cvt_pk_bf16_f32 v3, v4, v5
	v_pk_mul_f32 v[4:5], v[50:51], v[16:17] op_sel_hi:[1,0]
	s_nop 0
	v_pk_mul_f32 v[4:5], v[22:23], v[4:5]
	s_nop 0
	v_cvt_pk_bf16_f32 v11, v4, v5
	v_add_co_u32_e32 v4, vcc, 0x8018000, v24
	s_nop 1
	v_addc_co_u32_e32 v5, vcc, 0, v25, vcc
	global_store_dwordx4 v[4:5], v[0:3], off
	global_store_dwordx4 v[4:5], v[8:11], off offset:128
	s_branch .LBB0_306
